# P11: last k-iteration peeled; epilogue chunk-0 V^T fragments + LN gamma/beta loads issued in its phase 1 (counted waits 20), epilogue loads become moves
# speedup vs baseline: 1.0013x; 1.0013x over previous
;     __host__ __device__ bool next(int i, Unit& u) const {
;         const long L = (long)i * G + c; if (L >= nwg) return false;
;         int wgid = (int)L; { const int q = nwg / NXCD, r = nwg % NXCD, xcd = wgid % NXCD, off = wgid / NXCD; wgid = (xcd < r ? xcd * (q + 1) : r * (q + 1) + (xcd - r) * q) + off; }
;         const int nig = WGM * nN, gid = wgid / nig, fm = gid * WGM, gsz = (nM - fm) < WGM ? (nM - fm) : WGM;
;         u.pm = fm + ((wgid % nig) % gsz); u.pn = (wgid % nig) / gsz; return true;
; template <class Epi, class Sched, bool ALIGN_EPI = false, bool SP2 = false>
; __device__ __forceinline__ void gemm_phase(PG8_LAS unsigned char* lds, const Gemm g, const Sched& S, const Epi& E) {
;     ...
; #pragma unroll
;         for (int a = 0; a < 2; ++a)
; #pragma unroll
;             for (int b = 0; b < 2; ++b)
; #pragma unroll
;                 for (int m = 0; m < 4; ++m)
; #pragma unroll
;                     for (int n = 0; n < 2; ++n) acc[a][b][m][n] = (f32x4){0.f, 0.f, 0.f, 0.f};
.LBB0_1124:
	s_add_i32 s72, s72, 1
	s_mul_i32 s4, s72, s29
	s_mul_hi_u32 s5, s72, s28
	s_add_i32 s5, s5, s4
	s_mul_i32 s4, s72, s28
	s_add_u32 s26, s4, s2
	s_addc_u32 s27, s5, s3
	v_mov_b64_e32 v[2:3], 0x1800
	v_cmp_ge_i64_e32 vcc, s[26:27], v[2:3]
	v_cmp_lt_i64_e64 s[4:5], s[26:27], v[2:3]
	s_cbranch_vccnz .LBB0_1126
	s_ashr_i32 s22, s26, 31
	s_lshr_b32 s22, s22, 29
	s_add_i32 s22, s26, s22
	s_ashr_i32 s23, s22, 3
	s_and_b32 s22, s22, -8
	s_sub_i32 s22, s26, s22
	s_cmp_lt_i32 s22, 0
	s_cselect_b32 s24, s46, 0x300
	s_mul_i32 s22, s22, s24
	s_add_i32 s22, s22, s23
	s_mul_hi_i32 s23, s22, 0x2aaaaaab
	s_lshr_b32 s24, s23, 31
	s_ashr_i32 s23, s23, 7
	s_add_i32 s23, s23, s24
	s_lshl_b32 s24, s23, 3
	s_sub_i32 s25, 64, s24
	s_min_i32 s25, s25, 8
	s_abs_i32 s26, s25
	v_cvt_f32_u32_e32 v2, s26
	s_sub_i32 s34, 0, s26
	s_mulk_i32 s23, 0x300
	s_sub_i32 s23, s22, s23
	v_rcp_iflag_f32_e32 v2, v2
	s_abs_i32 s22, s23
	s_xor_b32 s27, s23, s25
	s_ashr_i32 s27, s27, 31
	v_mul_f32_e32 v2, 0x4f7ffffe, v2
	v_cvt_u32_f32_e32 v2, v2
	s_nop 0
	v_readfirstlane_b32 s35, v2
	s_mul_i32 s34, s34, s35
	s_mul_hi_u32 s34, s35, s34
	s_add_i32 s35, s35, s34
	s_mul_hi_u32 s34, s22, s35
	s_mul_i32 s35, s34, s26
	s_sub_i32 s22, s22, s35
	s_add_i32 s36, s34, 1
	s_sub_i32 s35, s22, s26
	s_cmp_ge_u32 s22, s26
	s_cselect_b32 s34, s36, s34
	s_cselect_b32 s22, s35, s22
	s_add_i32 s35, s34, 1
	s_cmp_ge_u32 s22, s26
	s_cselect_b32 s22, s35, s34
	s_xor_b32 s22, s22, s27
	s_sub_i32 s22, s22, s27
	s_mul_i32 s25, s22, s25
	s_sub_i32 s23, s23, s25
	s_add_i32 s24, s24, s23
.LBB0_1126:
	s_ashr_i32 s25, s24, 31
	s_lshl_b64 s[26:27], s[24:25], 21
	s_add_u32 s36, s54, s26
	s_addc_u32 s37, s55, s27
	s_and_b64 s[26:27], s[4:5], exec
	s_cselect_b32 s25, s37, s41
	s_cselect_b32 s26, s36, s40
	s_ashr_i32 s23, s22, 31
	s_lshl_b64 s[34:35], s[22:23], 21
	s_add_u32 s38, s19, s34
	s_addc_u32 s39, s21, s35
	s_and_b64 s[34:35], s[4:5], exec
	s_cselect_b32 s23, s39, s43
	s_cselect_b32 s27, s38, s42
	s_add_u32 s40, s40, 0x100080
	s_addc_u32 s41, s41, 0
	s_add_u32 s45, s42, 0x100
	v_mov_b32_e32 v2, 0
	s_addc_u32 s52, s43, 0
	s_mov_b32 s53, -2
	v_mov_b32_e32 v3, v2
	v_mov_b64_e32 v[4:5], 0
	v_mov_b64_e32 v[14:15], 0
	v_mov_b64_e32 v[16:17], 0
	v_mov_b64_e32 v[18:19], 0
	v_mov_b64_e32 v[20:21], 0
	v_mov_b64_e32 v[30:31], 0
	v_mov_b64_e32 v[32:33], 0
	v_mov_b64_e32 v[34:35], 0
	v_mov_b64_e32 v[36:37], 0
	v_mov_b64_e32 v[46:47], 0
	v_mov_b64_e32 v[48:49], 0
	v_mov_b64_e32 v[50:51], 0
	v_mov_b64_e32 v[52:53], 0
	v_mov_b64_e32 v[62:63], 0
	v_mov_b64_e32 v[64:65], 0
	v_mov_b64_e32 v[6:7], 0
	v_mov_b64_e32 v[8:9], 0
	v_mov_b64_e32 v[10:11], 0
	v_mov_b64_e32 v[12:13], 0
	v_mov_b64_e32 v[22:23], 0
	v_mov_b64_e32 v[24:25], 0
	v_mov_b64_e32 v[26:27], 0
	v_mov_b64_e32 v[28:29], 0
	v_mov_b64_e32 v[38:39], 0
	v_mov_b64_e32 v[40:41], 0
	v_mov_b64_e32 v[42:43], 0
	v_mov_b64_e32 v[44:45], 0
	v_mov_b64_e32 v[54:55], 0
	v_mov_b64_e32 v[56:57], 0
	v_mov_b64_e32 v[58:59], 0
	v_mov_b64_e32 v[60:61], 0
	v_mov_b64_e32 v[66:67], 0
	v_mov_b64_e32 v[68:69], 0
	v_mov_b64_e32 v[78:79], 0
	v_mov_b64_e32 v[80:81], 0
	v_mov_b64_e32 v[82:83], 0
	v_mov_b64_e32 v[84:85], 0
	v_mov_b64_e32 v[94:95], 0
	v_mov_b64_e32 v[96:97], 0
	v_mov_b64_e32 v[98:99], 0
	v_mov_b64_e32 v[100:101], 0
	v_mov_b64_e32 v[110:111], 0
	v_mov_b64_e32 v[112:113], 0
	v_mov_b64_e32 v[114:115], 0
	v_mov_b64_e32 v[116:117], 0
	v_mov_b64_e32 v[126:127], 0
	v_mov_b64_e32 v[128:129], 0
	v_mov_b64_e32 v[70:71], 0
	v_mov_b64_e32 v[72:73], 0
	v_mov_b64_e32 v[74:75], 0
	v_mov_b64_e32 v[76:77], 0
	v_mov_b64_e32 v[86:87], 0
	v_mov_b64_e32 v[88:89], 0
	v_mov_b64_e32 v[90:91], 0
	v_mov_b64_e32 v[92:93], 0
	v_mov_b64_e32 v[102:103], 0
	v_mov_b64_e32 v[104:105], 0
	v_mov_b64_e32 v[106:107], 0
	v_mov_b64_e32 v[108:109], 0
	v_mov_b64_e32 v[118:119], 0
	v_mov_b64_e32 v[120:121], 0
	v_mov_b64_e32 v[122:123], 0
	v_mov_b64_e32 v[124:125], 0
	v_readfirstlane_b32 s98, v0
	s_nop 1
	s_cmpk_gt_u32 s98, 0x7f
	s_cbranch_scc1 .Lp11_st_skip
	s_lshl_b32 s98, s6, 11
	s_add_u32 s100, s8, s98
	s_addc_u32 s101, s9, 0
	v_lshlrev_b32_e32 v200, 4, v0
	global_load_dwordx4 v[230:233], v200, s[100:101]

; #define PG8_STAGE(bufoff, gbase, voff) do { _Pragma("unroll") for (int _i = 0; _i < 2; ++_i) \
;         __builtin_amdgcn_global_load_lds((const unsigned*)((const char*)(gbase) + (voff)[_i]), (PG8_LAS unsigned*)(lds + (bufoff) + ldsw + _i * 8192), 16, 0, 0); } while (0)
; #define PG8_LDA(dst, b, h) do { _Pragma("unroll") for (int m = 0; m < 4; ++m) _Pragma("unroll") for (int k = 0; k < 2; ++k) dst[m][k] = *(const PG8_LAS bf16x8*)(lds + PG8_SA(b, h) + aoff + m * 2048 + k * 1024); } while (0)
; #define PG8_LDB(dst, b, h) do { _Pragma("unroll") for (int n = 0; n < 2; ++n) _Pragma("unroll") for (int k = 0; k < 2; ++k) dst[n][k] = *(const PG8_LAS bf16x8*)(lds + PG8_SB(b, h) + boff + n * 2048 + k * 1024); } while (0)
; #define PG8_MMA(ai, bj, At, Bt) do { __builtin_amdgcn_s_setprio(1); _Pragma("unroll") for (int m = 0; m < 4; ++m) _Pragma("unroll") for (int n = 0; n < 2; ++n) _Pragma("unroll") for (int k = 0; k < 2; ++k) \
;         acc[ai][bj][m][n] = __builtin_amdgcn_mfma_f32_16x16x32_bf16(Bt[n][k], At[m][k], acc[ai][bj][m][n], 0, 0, 0); __builtin_amdgcn_s_setprio(0); } while (0)
; #define PG8_WAIT_V(n) asm volatile("s_waitcnt vmcnt(" #n ")" ::: "memory")
; #define PG8_WAIT_L(n) asm volatile("s_waitcnt lgkmcnt(" #n ")" ::: "memory")
; #define PG8_BAR __builtin_amdgcn_s_barrier()
; #define PG8_SCHED __builtin_amdgcn_sched_barrier(0)
; template <class Epi, class Sched, bool ALIGN_EPI = false, bool SP2 = false>
; __device__ __forceinline__ void gemm_phase(PG8_LAS unsigned char* lds, const Gemm g, const Sched& S, const Epi& E) {
;     ...
;             PG8_LDB(B0, 0, 0); PG8_LDB(B1, 0, 1); PG8_SCHED; PG8_LDA(At, 0, 0); PG8_STAGE(PG8_SA(1, 1), a1 + hstepA, voffA);
;             PG8_WAIT_V(8); PG8_WAIT_L(0); PG8_BAR; PG8_MMA(0, 0, At, B0); PG8_MMA(0, 1, At, B1); PG8_BAR; PG8_SCHED;
;             PG8_LDA(At, 0, 1); PG8_STAGE(PG8_SB(0, 0), b2, voffB); PG8_STAGE(PG8_SB(0, 1), b2 + hstepB, voffB); PG8_STAGE(PG8_SA(0, 0), a2, voffA);
;             PG8_WAIT_V(8); PG8_WAIT_L(0); PG8_BAR; PG8_MMA(1, 0, At, B0); PG8_MMA(1, 1, At, B1); PG8_BAR; PG8_SCHED;
.Lsp_LBB0_1127:
.LBB0_1127:
	ds_read_b128 v[130:133], v203
	ds_read_b128 v[134:137], v203 offset:1024
	ds_read_b128 v[138:141], v203 offset:2048
	ds_read_b128 v[142:145], v203 offset:3072
	ds_read_b128 v[146:149], v205
	ds_read_b128 v[150:153], v205 offset:1024
	ds_read_b128 v[154:157], v205 offset:2048
	ds_read_b128 v[158:161], v205 offset:3072
	s_add_u32 s34, s40, 0xfff00080
	s_addc_u32 s35, s41, -1
	s_cmp_eq_u32 s53, 60
	s_cselect_b32 s35, s25, s35
	s_cselect_b32 s34, s26, s34
	s_cselect_b32 s43, s23, s52
	s_cselect_b32 s42, s27, s45
	s_add_i32 m0, s47, 0xc000
	ds_read_b128 v[162:165], v207
	ds_read_b128 v[166:169], v207 offset:1024
	ds_read_b128 v[170:173], v207 offset:2048
	ds_read_b128 v[174:177], v207 offset:3072
	ds_read_b128 v[196:199], v207 offset:4096
	ds_read_b128 v[208:211], v207 offset:5120
	ds_read_b128 v[212:215], v207 offset:6144
	ds_read_b128 v[216:219], v207 offset:7168
	global_load_lds_dwordx4 v188, s[40:41]
	s_add_i32 m0, s47, 0xe000
	s_nop 0
	global_load_lds_dwordx4 v190, s[40:41]
	s_waitcnt vmcnt(8)
	s_waitcnt lgkmcnt(0)
	s_barrier
	s_waitcnt lgkmcnt(0)
	v_mfma_f32_16x16x32_bf16 v[122:125], v[130:133], v[162:165], v[122:125]
	v_mfma_f32_16x16x32_bf16 v[118:121], v[138:141], v[162:165], v[118:121]
	v_mfma_f32_16x16x32_bf16 v[106:109], v[130:133], v[170:173], v[106:109]
	v_mfma_f32_16x16x32_bf16 v[102:105], v[138:141], v[170:173], v[102:105]
	v_mfma_f32_16x16x32_bf16 v[90:93], v[130:133], v[196:199], v[90:93]
	v_mfma_f32_16x16x32_bf16 v[86:89], v[138:141], v[196:199], v[86:89]
	v_mfma_f32_16x16x32_bf16 v[74:77], v[130:133], v[212:215], v[74:77]
	v_mfma_f32_16x16x32_bf16 v[70:73], v[138:141], v[212:215], v[70:73]
	v_mfma_f32_16x16x32_bf16 v[122:125], v[134:137], v[166:169], v[122:125]
	v_mfma_f32_16x16x32_bf16 v[118:121], v[142:145], v[166:169], v[118:121]
	v_mfma_f32_16x16x32_bf16 v[106:109], v[134:137], v[174:177], v[106:109]
	v_mfma_f32_16x16x32_bf16 v[102:105], v[142:145], v[174:177], v[102:105]
	v_mfma_f32_16x16x32_bf16 v[90:93], v[134:137], v[208:211], v[90:93]
	v_mfma_f32_16x16x32_bf16 v[86:89], v[142:145], v[208:211], v[86:89]
	v_mfma_f32_16x16x32_bf16 v[74:77], v[134:137], v[216:219], v[74:77]
	v_mfma_f32_16x16x32_bf16 v[70:73], v[142:145], v[216:219], v[70:73]
	v_mfma_f32_16x16x32_bf16 v[126:129], v[146:149], v[162:165], v[126:129]
	v_mfma_f32_16x16x32_bf16 v[114:117], v[154:157], v[162:165], v[114:117]
	v_mfma_f32_16x16x32_bf16 v[110:113], v[146:149], v[170:173], v[110:113]
	v_mfma_f32_16x16x32_bf16 v[98:101], v[154:157], v[170:173], v[98:101]
	v_mfma_f32_16x16x32_bf16 v[94:97], v[146:149], v[196:199], v[94:97]
	v_mfma_f32_16x16x32_bf16 v[82:85], v[154:157], v[196:199], v[82:85]
	v_mfma_f32_16x16x32_bf16 v[78:81], v[146:149], v[212:215], v[78:81]
	v_mfma_f32_16x16x32_bf16 v[66:69], v[154:157], v[212:215], v[66:69]
	v_mfma_f32_16x16x32_bf16 v[126:129], v[150:153], v[166:169], v[126:129]
	v_mfma_f32_16x16x32_bf16 v[114:117], v[158:161], v[166:169], v[114:117]
	v_mfma_f32_16x16x32_bf16 v[110:113], v[150:153], v[174:177], v[110:113]
	v_mfma_f32_16x16x32_bf16 v[98:101], v[158:161], v[174:177], v[98:101]
	v_mfma_f32_16x16x32_bf16 v[94:97], v[150:153], v[208:211], v[94:97]
	v_mfma_f32_16x16x32_bf16 v[82:85], v[158:161], v[208:211], v[82:85]
	v_mfma_f32_16x16x32_bf16 v[78:81], v[150:153], v[216:219], v[78:81]
	v_mfma_f32_16x16x32_bf16 v[66:69], v[158:161], v[216:219], v[66:69]
	s_barrier
	s_add_i32 s73, s68, s17
	s_add_u32 s98, s42, 0x80
	s_addc_u32 s99, s43, 0
	s_add_u32 s100, s34, 0x80
	s_addc_u32 s101, s35, 0
	s_mov_b32 m0, s73
	ds_read_b128 v[162:165], v207 offset:16384
	ds_read_b128 v[166:169], v207 offset:17408
	ds_read_b128 v[170:173], v207 offset:18432
	ds_read_b128 v[174:177], v207 offset:19456
	ds_read_b128 v[196:199], v207 offset:20480
	ds_read_b128 v[208:211], v207 offset:21504
	ds_read_b128 v[212:215], v207 offset:22528
	ds_read_b128 v[216:219], v207 offset:23552
	global_load_lds_dwordx4 v182, s[42:43]
	s_add_i32 m0, s73, 0x2000
	s_add_u32 s74, s42, 0x100000
	s_addc_u32 s75, s43, 0
	s_add_i32 s73, s69, s17
	global_load_lds_dwordx4 v178, s[42:43]
	s_mov_b32 m0, s73
	s_nop 0
	global_load_lds_dwordx4 v182, s[74:75]
	s_add_i32 m0, s73, 0x2000
	s_nop 0
	global_load_lds_dwordx4 v178, s[74:75]
	s_mov_b32 m0, s47
	s_nop 0
	global_load_lds_dwordx4 v184, s[34:35]
	s_mov_b32 m0, s48
	s_nop 0
	global_load_lds_dwordx4 v180, s[34:35]
	s_waitcnt vmcnt(8)
	s_waitcnt lgkmcnt(0)
	s_barrier
	s_waitcnt lgkmcnt(0)
	v_mfma_f32_16x16x32_bf16 v[58:61], v[130:133], v[162:165], v[58:61]
	v_mfma_f32_16x16x32_bf16 v[54:57], v[138:141], v[162:165], v[54:57]
	v_mfma_f32_16x16x32_bf16 v[42:45], v[130:133], v[170:173], v[42:45]
	v_mfma_f32_16x16x32_bf16 v[38:41], v[138:141], v[170:173], v[38:41]
	v_mfma_f32_16x16x32_bf16 v[26:29], v[130:133], v[196:199], v[26:29]
	v_mfma_f32_16x16x32_bf16 v[22:25], v[138:141], v[196:199], v[22:25]
	v_mfma_f32_16x16x32_bf16 v[10:13], v[130:133], v[212:215], v[10:13]
	v_mfma_f32_16x16x32_bf16 v[6:9], v[138:141], v[212:215], v[6:9]
	v_mfma_f32_16x16x32_bf16 v[58:61], v[134:137], v[166:169], v[58:61]
	v_mfma_f32_16x16x32_bf16 v[54:57], v[142:145], v[166:169], v[54:57]
	v_mfma_f32_16x16x32_bf16 v[42:45], v[134:137], v[174:177], v[42:45]
	v_mfma_f32_16x16x32_bf16 v[38:41], v[142:145], v[174:177], v[38:41]
	v_mfma_f32_16x16x32_bf16 v[26:29], v[134:137], v[208:211], v[26:29]
	v_mfma_f32_16x16x32_bf16 v[22:25], v[142:145], v[208:211], v[22:25]
	v_mfma_f32_16x16x32_bf16 v[10:13], v[134:137], v[216:219], v[10:13]
	v_mfma_f32_16x16x32_bf16 v[6:9], v[142:145], v[216:219], v[6:9]
	v_mfma_f32_16x16x32_bf16 v[62:65], v[146:149], v[162:165], v[62:65]
	v_mfma_f32_16x16x32_bf16 v[50:53], v[154:157], v[162:165], v[50:53]
	v_mfma_f32_16x16x32_bf16 v[46:49], v[146:149], v[170:173], v[46:49]
	v_mfma_f32_16x16x32_bf16 v[34:37], v[154:157], v[170:173], v[34:37]
	v_mfma_f32_16x16x32_bf16 v[30:33], v[146:149], v[196:199], v[30:33]
	v_mfma_f32_16x16x32_bf16 v[18:21], v[154:157], v[196:199], v[18:21]
	v_mfma_f32_16x16x32_bf16 v[14:17], v[146:149], v[212:215], v[14:17]
	v_mfma_f32_16x16x32_bf16 v[2:5], v[154:157], v[212:215], v[2:5]
	v_mfma_f32_16x16x32_bf16 v[62:65], v[150:153], v[166:169], v[62:65]
	v_mfma_f32_16x16x32_bf16 v[50:53], v[158:161], v[166:169], v[50:53]
	v_mfma_f32_16x16x32_bf16 v[46:49], v[150:153], v[174:177], v[46:49]
	v_mfma_f32_16x16x32_bf16 v[34:37], v[158:161], v[174:177], v[34:37]
	v_mfma_f32_16x16x32_bf16 v[30:33], v[150:153], v[208:211], v[30:33]
	v_mfma_f32_16x16x32_bf16 v[18:21], v[158:161], v[208:211], v[18:21]
	v_mfma_f32_16x16x32_bf16 v[14:17], v[150:153], v[216:219], v[14:17]
	v_mfma_f32_16x16x32_bf16 v[2:5], v[158:161], v[216:219], v[2:5]
	s_barrier
; #define PG8_STAGE(bufoff, gbase, voff) do { _Pragma("unroll") for (int _i = 0; _i < 2; ++_i) \
;         __builtin_amdgcn_global_load_lds((const unsigned*)((const char*)(gbase) + (voff)[_i]), (PG8_LAS unsigned*)(lds + (bufoff) + ldsw + _i * 8192), 16, 0, 0); } while (0)
; #define PG8_LDA(dst, b, h) do { _Pragma("unroll") for (int m = 0; m < 4; ++m) _Pragma("unroll") for (int k = 0; k < 2; ++k) dst[m][k] = *(const PG8_LAS bf16x8*)(lds + PG8_SA(b, h) + aoff + m * 2048 + k * 1024); } while (0)
; #define PG8_LDB(dst, b, h) do { _Pragma("unroll") for (int n = 0; n < 2; ++n) _Pragma("unroll") for (int k = 0; k < 2; ++k) dst[n][k] = *(const PG8_LAS bf16x8*)(lds + PG8_SB(b, h) + boff + n * 2048 + k * 1024); } while (0)
; #define PG8_MMA(ai, bj, At, Bt) do { __builtin_amdgcn_s_setprio(1); _Pragma("unroll") for (int m = 0; m < 4; ++m) _Pragma("unroll") for (int n = 0; n < 2; ++n) _Pragma("unroll") for (int k = 0; k < 2; ++k) \
;         acc[ai][bj][m][n] = __builtin_amdgcn_mfma_f32_16x16x32_bf16(Bt[n][k], At[m][k], acc[ai][bj][m][n], 0, 0, 0); __builtin_amdgcn_s_setprio(0); } while (0)
; #define PG8_WAIT_V(n) asm volatile("s_waitcnt vmcnt(" #n ")" ::: "memory")
; #define PG8_WAIT_L(n) asm volatile("s_waitcnt lgkmcnt(" #n ")" ::: "memory")
; #define PG8_BAR __builtin_amdgcn_s_barrier()
; #define PG8_SCHED __builtin_amdgcn_sched_barrier(0)
; template <class Epi, class Sched, bool ALIGN_EPI = false, bool SP2 = false>
; __device__ __forceinline__ void gemm_phase(PG8_LAS unsigned char* lds, const Gemm g, const Sched& S, const Epi& E) {
;     ...
;             PG8_LDB(B0, 1, 0); PG8_LDB(B1, 1, 1); PG8_SCHED; PG8_LDA(At, 1, 0); PG8_STAGE(PG8_SA(0, 1), a2 + hstepA, voffA);
;             PG8_WAIT_V(8); PG8_WAIT_L(0); PG8_BAR; PG8_MMA(0, 0, At, B0); PG8_MMA(0, 1, At, B1); PG8_BAR; PG8_SCHED;
;             PG8_LDA(At, 1, 1); PG8_STAGE(PG8_SB(1, 0), b3, voffB); PG8_STAGE(PG8_SB(1, 1), b3 + hstepB, voffB); PG8_STAGE(PG8_SA(1, 0), a3, voffA);
;             PG8_WAIT_V(8); PG8_WAIT_L(0); PG8_BAR; PG8_MMA(1, 0, At, B0); PG8_MMA(1, 1, At, B1); PG8_BAR; PG8_SCHED;
	s_add_i32 s73, 0, 0x18000
	s_add_i32 s74, 0, 0x1c000
	v_add_u32_e32 v142, s73, v1
	v_add_u32_e32 v158, s74, v1
	ds_read_b128 v[130:133], v142
	ds_read_b128 v[134:137], v142 offset:1024
	ds_read_b128 v[138:141], v142 offset:2048
	ds_read_b128 v[142:145], v142 offset:3072
	ds_read_b128 v[146:149], v158
	ds_read_b128 v[150:153], v158 offset:1024
	ds_read_b128 v[154:157], v158 offset:2048
	ds_read_b128 v[158:161], v158 offset:3072
	s_add_u32 s34, s34, 0x100000
	s_addc_u32 s35, s35, 0
	s_mov_b32 m0, s49
	ds_read_b128 v[162:165], v207 offset:32768
	ds_read_b128 v[166:169], v207 offset:33792
	ds_read_b128 v[170:173], v207 offset:34816
	ds_read_b128 v[174:177], v207 offset:35840
	ds_read_b128 v[196:199], v207 offset:36864
	ds_read_b128 v[208:211], v207 offset:37888
	ds_read_b128 v[212:215], v207 offset:38912
	ds_read_b128 v[216:219], v207 offset:39936
	global_load_lds_dwordx4 v184, s[34:35]
	s_mov_b32 m0, s60
	s_nop 0
	global_load_lds_dwordx4 v180, s[34:35]
	s_waitcnt vmcnt(8)
	s_waitcnt lgkmcnt(0)
	s_barrier
	s_waitcnt lgkmcnt(0)
	v_mfma_f32_16x16x32_bf16 v[122:125], v[130:133], v[162:165], v[122:125]
	v_mfma_f32_16x16x32_bf16 v[118:121], v[138:141], v[162:165], v[118:121]
	v_mfma_f32_16x16x32_bf16 v[106:109], v[130:133], v[170:173], v[106:109]
	v_mfma_f32_16x16x32_bf16 v[102:105], v[138:141], v[170:173], v[102:105]
	v_mfma_f32_16x16x32_bf16 v[90:93], v[130:133], v[196:199], v[90:93]
	v_mfma_f32_16x16x32_bf16 v[86:89], v[138:141], v[196:199], v[86:89]
	v_mfma_f32_16x16x32_bf16 v[74:77], v[130:133], v[212:215], v[74:77]
	v_mfma_f32_16x16x32_bf16 v[70:73], v[138:141], v[212:215], v[70:73]
	v_mfma_f32_16x16x32_bf16 v[122:125], v[134:137], v[166:169], v[122:125]
	v_mfma_f32_16x16x32_bf16 v[118:121], v[142:145], v[166:169], v[118:121]
	v_mfma_f32_16x16x32_bf16 v[106:109], v[134:137], v[174:177], v[106:109]
	v_mfma_f32_16x16x32_bf16 v[102:105], v[142:145], v[174:177], v[102:105]
	v_mfma_f32_16x16x32_bf16 v[90:93], v[134:137], v[208:211], v[90:93]
	v_mfma_f32_16x16x32_bf16 v[86:89], v[142:145], v[208:211], v[86:89]
	v_mfma_f32_16x16x32_bf16 v[74:77], v[134:137], v[216:219], v[74:77]
	v_mfma_f32_16x16x32_bf16 v[70:73], v[142:145], v[216:219], v[70:73]
	v_mfma_f32_16x16x32_bf16 v[126:129], v[146:149], v[162:165], v[126:129]
	v_mfma_f32_16x16x32_bf16 v[114:117], v[154:157], v[162:165], v[114:117]
	v_mfma_f32_16x16x32_bf16 v[110:113], v[146:149], v[170:173], v[110:113]
	v_mfma_f32_16x16x32_bf16 v[98:101], v[154:157], v[170:173], v[98:101]
	v_mfma_f32_16x16x32_bf16 v[94:97], v[146:149], v[196:199], v[94:97]
	v_mfma_f32_16x16x32_bf16 v[82:85], v[154:157], v[196:199], v[82:85]
	v_mfma_f32_16x16x32_bf16 v[78:81], v[146:149], v[212:215], v[78:81]
	v_mfma_f32_16x16x32_bf16 v[66:69], v[154:157], v[212:215], v[66:69]
	v_mfma_f32_16x16x32_bf16 v[126:129], v[150:153], v[166:169], v[126:129]
	v_mfma_f32_16x16x32_bf16 v[114:117], v[158:161], v[166:169], v[114:117]
	v_mfma_f32_16x16x32_bf16 v[110:113], v[150:153], v[174:177], v[110:113]
	v_mfma_f32_16x16x32_bf16 v[98:101], v[158:161], v[174:177], v[98:101]
	v_mfma_f32_16x16x32_bf16 v[94:97], v[150:153], v[208:211], v[94:97]
	v_mfma_f32_16x16x32_bf16 v[82:85], v[158:161], v[208:211], v[82:85]
	v_mfma_f32_16x16x32_bf16 v[78:81], v[150:153], v[216:219], v[78:81]
	v_mfma_f32_16x16x32_bf16 v[66:69], v[158:161], v[216:219], v[66:69]
	s_barrier
	s_add_i32 s34, s73, s17
	s_mov_b32 m0, s34
	ds_read_b128 v[162:165], v207 offset:49152
	ds_read_b128 v[166:169], v207 offset:50176
	ds_read_b128 v[170:173], v207 offset:51200
	ds_read_b128 v[174:177], v207 offset:52224
	ds_read_b128 v[196:199], v207 offset:53248
	ds_read_b128 v[208:211], v207 offset:54272
	ds_read_b128 v[212:215], v207 offset:55296
	ds_read_b128 v[216:219], v207 offset:56320
	global_load_lds_dwordx4 v182, s[98:99]
	s_add_i32 m0, s34, 0x2000
	s_add_u32 s34, s42, 0x100080
	s_addc_u32 s35, s43, 0
	s_add_i32 s42, s74, s17
	global_load_lds_dwordx4 v178, s[98:99]
	s_mov_b32 m0, s42
	s_nop 0
	global_load_lds_dwordx4 v182, s[34:35]
	s_add_i32 m0, s42, 0x2000
	s_nop 0
	global_load_lds_dwordx4 v178, s[34:35]
	s_mov_b32 m0, s64
	s_nop 0
	global_load_lds_dwordx4 v184, s[100:101]
	s_mov_b32 m0, s65
	s_nop 0
	global_load_lds_dwordx4 v180, s[100:101]
	s_waitcnt vmcnt(8)
	s_waitcnt lgkmcnt(0)
	s_barrier
	s_waitcnt lgkmcnt(0)
	v_mfma_f32_16x16x32_bf16 v[58:61], v[130:133], v[162:165], v[58:61]
	v_mfma_f32_16x16x32_bf16 v[54:57], v[138:141], v[162:165], v[54:57]
	v_mfma_f32_16x16x32_bf16 v[42:45], v[130:133], v[170:173], v[42:45]
	v_mfma_f32_16x16x32_bf16 v[38:41], v[138:141], v[170:173], v[38:41]
	v_mfma_f32_16x16x32_bf16 v[26:29], v[130:133], v[196:199], v[26:29]
	v_mfma_f32_16x16x32_bf16 v[22:25], v[138:141], v[196:199], v[22:25]
	v_mfma_f32_16x16x32_bf16 v[10:13], v[130:133], v[212:215], v[10:13]
	v_mfma_f32_16x16x32_bf16 v[6:9], v[138:141], v[212:215], v[6:9]
	v_mfma_f32_16x16x32_bf16 v[58:61], v[134:137], v[166:169], v[58:61]
	v_mfma_f32_16x16x32_bf16 v[54:57], v[142:145], v[166:169], v[54:57]
	v_mfma_f32_16x16x32_bf16 v[42:45], v[134:137], v[174:177], v[42:45]
	v_mfma_f32_16x16x32_bf16 v[38:41], v[142:145], v[174:177], v[38:41]
	v_mfma_f32_16x16x32_bf16 v[26:29], v[134:137], v[208:211], v[26:29]
	v_mfma_f32_16x16x32_bf16 v[22:25], v[142:145], v[208:211], v[22:25]
	v_mfma_f32_16x16x32_bf16 v[10:13], v[134:137], v[216:219], v[10:13]
	v_mfma_f32_16x16x32_bf16 v[6:9], v[142:145], v[216:219], v[6:9]
	v_mfma_f32_16x16x32_bf16 v[62:65], v[146:149], v[162:165], v[62:65]
	v_mfma_f32_16x16x32_bf16 v[50:53], v[154:157], v[162:165], v[50:53]
	v_mfma_f32_16x16x32_bf16 v[46:49], v[146:149], v[170:173], v[46:49]
	v_mfma_f32_16x16x32_bf16 v[34:37], v[154:157], v[170:173], v[34:37]
	v_mfma_f32_16x16x32_bf16 v[30:33], v[146:149], v[196:199], v[30:33]
	v_mfma_f32_16x16x32_bf16 v[18:21], v[154:157], v[196:199], v[18:21]
	v_mfma_f32_16x16x32_bf16 v[14:17], v[146:149], v[212:215], v[14:17]
	v_mfma_f32_16x16x32_bf16 v[2:5], v[154:157], v[212:215], v[2:5]
	v_mfma_f32_16x16x32_bf16 v[62:65], v[150:153], v[166:169], v[62:65]
	v_mfma_f32_16x16x32_bf16 v[50:53], v[158:161], v[166:169], v[50:53]
	v_mfma_f32_16x16x32_bf16 v[46:49], v[150:153], v[174:177], v[46:49]
	v_mfma_f32_16x16x32_bf16 v[34:37], v[158:161], v[174:177], v[34:37]
	v_mfma_f32_16x16x32_bf16 v[30:33], v[150:153], v[208:211], v[30:33]
	v_mfma_f32_16x16x32_bf16 v[18:21], v[158:161], v[208:211], v[18:21]
	v_mfma_f32_16x16x32_bf16 v[14:17], v[150:153], v[216:219], v[14:17]
	v_mfma_f32_16x16x32_bf16 v[2:5], v[158:161], v[216:219], v[2:5]
	s_barrier
; #define PG8_STAGE(bufoff, gbase, voff) do { _Pragma("unroll") for (int _i = 0; _i < 2; ++_i) \
;         __builtin_amdgcn_global_load_lds((const unsigned*)((const char*)(gbase) + (voff)[_i]), (PG8_LAS unsigned*)(lds + (bufoff) + ldsw + _i * 8192), 16, 0, 0); } while (0)
; #define PG8_LDA(dst, b, h) do { _Pragma("unroll") for (int m = 0; m < 4; ++m) _Pragma("unroll") for (int k = 0; k < 2; ++k) dst[m][k] = *(const PG8_LAS bf16x8*)(lds + PG8_SA(b, h) + aoff + m * 2048 + k * 1024); } while (0)
; #define PG8_LDB(dst, b, h) do { _Pragma("unroll") for (int n = 0; n < 2; ++n) _Pragma("unroll") for (int k = 0; k < 2; ++k) dst[n][k] = *(const PG8_LAS bf16x8*)(lds + PG8_SB(b, h) + boff + n * 2048 + k * 1024); } while (0)
; #define PG8_MMA(ai, bj, At, Bt) do { __builtin_amdgcn_s_setprio(1); _Pragma("unroll") for (int m = 0; m < 4; ++m) _Pragma("unroll") for (int n = 0; n < 2; ++n) _Pragma("unroll") for (int k = 0; k < 2; ++k) \
;         acc[ai][bj][m][n] = __builtin_amdgcn_mfma_f32_16x16x32_bf16(Bt[n][k], At[m][k], acc[ai][bj][m][n], 0, 0, 0); __builtin_amdgcn_s_setprio(0); } while (0)
; template <class Epi, class Sched, bool ALIGN_EPI = false, bool SP2 = false>
; __device__ __forceinline__ void gemm_phase(PG8_LAS unsigned char* lds, const Gemm g, const Sched& S, const Epi& E) {
;     ...
;             PG8_LDB(B0, 0, 0); PG8_LDB(B1, 0, 1); PG8_SCHED; PG8_LDA(At, 0, 0); PG8_STAGE(PG8_SA(1, 1), a1 + hstepA, voffA);
;             PG8_WAIT_V(8); PG8_WAIT_L(0); PG8_BAR; PG8_MMA(0, 0, At, B0); PG8_MMA(0, 1, At, B1); PG8_BAR; PG8_SCHED;
;             PG8_LDA(At, 0, 1); PG8_STAGE(PG8_SB(0, 0), b2, voffB); PG8_STAGE(PG8_SB(0, 1), b2 + hstepB, voffB); PG8_STAGE(PG8_SA(0, 0), a2, voffA);
;     __device__ __forceinline__ void operator()(const af4 (&acc)[2][2][4][2], const pg8::Unit& u, int wr_, int wc_, int fr_, int fq_) const {
;     ...
;         const int chl = chbase + 32 * wc + 8 * (fr >> 2) + (fr & 3);
;         float lg[2], lb[2];
; #pragma unroll
;         for (int n = 0; n < 2; ++n) { lg[n] = lng[chl + 4 * n]; lb[n] = lnb[chl + 4 * n]; }
;         v4u raw[2][4];
;         auto load_raw = [&](int ai) {
; #pragma unroll
;             for (int ks = 0; ks < 4; ++ks)
; #pragma unroll
;                 for (int n = 0; n < 2; ++n) raw[n][ks] = *(const GAS v4u*)(VT + (size_t)(chl + 4 * n) * MLAT + u.pm * 256 + ai * 128 + 32 * ks + 8 * fq);
;         };
	s_add_i32 s53, s53, 2
	s_add_u32 s40, s40, 0x100
	s_addc_u32 s41, s41, 0
	s_add_u32 s45, s45, 0x100
	s_addc_u32 s52, s52, 0
	s_cmp_gt_u32 s53, 59
	s_cbranch_scc0 .LBB0_1127
	ds_read_b128 v[130:133], v203
	ds_read_b128 v[134:137], v203 offset:1024
	ds_read_b128 v[138:141], v203 offset:2048
	ds_read_b128 v[142:145], v203 offset:3072
	ds_read_b128 v[146:149], v205
	ds_read_b128 v[150:153], v205 offset:1024
	ds_read_b128 v[154:157], v205 offset:2048
	ds_read_b128 v[158:161], v205 offset:3072
	s_add_u32 s34, s40, 0xfff00080
	s_addc_u32 s35, s41, -1
	s_cmp_eq_u32 s53, 60
	s_cselect_b32 s35, s25, s35
	s_cselect_b32 s34, s26, s34
	s_cselect_b32 s43, s23, s52
	s_cselect_b32 s42, s27, s45
	s_add_i32 m0, s47, 0xc000
	ds_read_b128 v[162:165], v207
	ds_read_b128 v[166:169], v207 offset:1024
	ds_read_b128 v[170:173], v207 offset:2048
	ds_read_b128 v[174:177], v207 offset:3072
	ds_read_b128 v[196:199], v207 offset:4096
	ds_read_b128 v[208:211], v207 offset:5120
	ds_read_b128 v[212:215], v207 offset:6144
	ds_read_b128 v[216:219], v207 offset:7168
	global_load_lds_dwordx4 v188, s[40:41]
	s_add_i32 m0, s47, 0xe000
	s_nop 0
	global_load_lds_dwordx4 v190, s[40:41]
	v_readlane_b32 s98, v254, 12
	v_readlane_b32 s99, v254, 13
	v_readlane_b32 s100, v254, 14
	v_readlane_b32 s101, v254, 15
	v_readfirstlane_b32 s73, v0
	v_lshlrev_b32_e32 v200, 1, v0
	v_and_b32_e32 v201, 3, v0
	v_and_b32_e32 v200, 24, v200
	s_lshl_b32 s74, s44, 7
	v_or3_b32 v200, v201, v200, s74
	s_lshr_b32 s73, s73, 1
	s_and_b32 s73, s73, 0x60
	v_or_b32_e32 v200, s73, v200
	v_lshlrev_b32_e32 v204, 2, v200
	v_lshrrev_b32_e32 v202, 1, v0
	v_and_b32_e32 v202, 24, v202
	v_lshlrev_b32_e32 v200, 15, v200
	v_lshl_add_u32 v200, v202, 1, v200
	s_lshl_b32 s74, s6, 9
	v_add_u32_e32 v200, s74, v200
	v_add_u32_e32 v201, 0x20000, v200
	global_load_dword v179, v204, s[98:99]
	global_load_dword v181, v204, s[98:99] offset:16
	global_load_dword v183, v204, s[100:101]
	global_load_dword v185, v204, s[100:101] offset:16
	global_load_dwordx4 v[192:195], v200, s[50:51]
	global_load_dwordx4 v[222:225], v201, s[50:51]
	global_load_dwordx4 v[226:229], v200, s[50:51] offset:64
	global_load_dwordx4 v[234:237], v200, s[50:51] offset:128
	global_load_dwordx4 v[238:241], v200, s[50:51] offset:192
	global_load_dwordx4 v[242:245], v201, s[50:51] offset:64
	global_load_dwordx4 v[246:249], v201, s[50:51] offset:128
	global_load_dwordx4 v[250:253], v201, s[50:51] offset:192
	s_waitcnt vmcnt(20)
	s_waitcnt lgkmcnt(0)
	s_barrier
	s_waitcnt lgkmcnt(0)
	v_mfma_f32_16x16x32_bf16 v[122:125], v[130:133], v[162:165], v[122:125]
	v_mfma_f32_16x16x32_bf16 v[118:121], v[138:141], v[162:165], v[118:121]
	v_mfma_f32_16x16x32_bf16 v[106:109], v[130:133], v[170:173], v[106:109]
	v_mfma_f32_16x16x32_bf16 v[102:105], v[138:141], v[170:173], v[102:105]
	v_mfma_f32_16x16x32_bf16 v[90:93], v[130:133], v[196:199], v[90:93]
	v_mfma_f32_16x16x32_bf16 v[86:89], v[138:141], v[196:199], v[86:89]
	v_mfma_f32_16x16x32_bf16 v[74:77], v[130:133], v[212:215], v[74:77]
	v_mfma_f32_16x16x32_bf16 v[70:73], v[138:141], v[212:215], v[70:73]
	v_mfma_f32_16x16x32_bf16 v[122:125], v[134:137], v[166:169], v[122:125]
	v_mfma_f32_16x16x32_bf16 v[118:121], v[142:145], v[166:169], v[118:121]
	v_mfma_f32_16x16x32_bf16 v[106:109], v[134:137], v[174:177], v[106:109]
	v_mfma_f32_16x16x32_bf16 v[102:105], v[142:145], v[174:177], v[102:105]
	v_mfma_f32_16x16x32_bf16 v[90:93], v[134:137], v[208:211], v[90:93]
	v_mfma_f32_16x16x32_bf16 v[86:89], v[142:145], v[208:211], v[86:89]
	v_mfma_f32_16x16x32_bf16 v[74:77], v[134:137], v[216:219], v[74:77]
	v_mfma_f32_16x16x32_bf16 v[70:73], v[142:145], v[216:219], v[70:73]
	v_mfma_f32_16x16x32_bf16 v[126:129], v[146:149], v[162:165], v[126:129]
	v_mfma_f32_16x16x32_bf16 v[114:117], v[154:157], v[162:165], v[114:117]
	v_mfma_f32_16x16x32_bf16 v[110:113], v[146:149], v[170:173], v[110:113]
	v_mfma_f32_16x16x32_bf16 v[98:101], v[154:157], v[170:173], v[98:101]
	v_mfma_f32_16x16x32_bf16 v[94:97], v[146:149], v[196:199], v[94:97]
	v_mfma_f32_16x16x32_bf16 v[82:85], v[154:157], v[196:199], v[82:85]
	v_mfma_f32_16x16x32_bf16 v[78:81], v[146:149], v[212:215], v[78:81]
	v_mfma_f32_16x16x32_bf16 v[66:69], v[154:157], v[212:215], v[66:69]
	v_mfma_f32_16x16x32_bf16 v[126:129], v[150:153], v[166:169], v[126:129]
	v_mfma_f32_16x16x32_bf16 v[114:117], v[158:161], v[166:169], v[114:117]
	v_mfma_f32_16x16x32_bf16 v[110:113], v[150:153], v[174:177], v[110:113]
	v_mfma_f32_16x16x32_bf16 v[98:101], v[158:161], v[174:177], v[98:101]
	v_mfma_f32_16x16x32_bf16 v[94:97], v[150:153], v[208:211], v[94:97]
	v_mfma_f32_16x16x32_bf16 v[82:85], v[158:161], v[208:211], v[82:85]
	v_mfma_f32_16x16x32_bf16 v[78:81], v[150:153], v[216:219], v[78:81]
	v_mfma_f32_16x16x32_bf16 v[66:69], v[158:161], v[216:219], v[66:69]
	s_barrier
	s_add_i32 s73, s68, s17
	s_add_u32 s98, s42, 0x80
	s_addc_u32 s99, s43, 0
	s_add_u32 s100, s34, 0x80
	s_addc_u32 s101, s35, 0
	s_mov_b32 m0, s73
	ds_read_b128 v[162:165], v207 offset:16384
	ds_read_b128 v[166:169], v207 offset:17408
	ds_read_b128 v[170:173], v207 offset:18432
	ds_read_b128 v[174:177], v207 offset:19456
	ds_read_b128 v[196:199], v207 offset:20480
	ds_read_b128 v[208:211], v207 offset:21504
	ds_read_b128 v[212:215], v207 offset:22528
	ds_read_b128 v[216:219], v207 offset:23552
	global_load_lds_dwordx4 v182, s[42:43]
	s_add_i32 m0, s73, 0x2000
	s_add_u32 s74, s42, 0x100000
	s_addc_u32 s75, s43, 0
	s_add_i32 s73, s69, s17
	global_load_lds_dwordx4 v178, s[42:43]
	s_mov_b32 m0, s73
	s_nop 0
	global_load_lds_dwordx4 v182, s[74:75]
	s_add_i32 m0, s73, 0x2000
	s_nop 0
	global_load_lds_dwordx4 v178, s[74:75]
	s_mov_b32 m0, s47
	s_nop 0
	global_load_lds_dwordx4 v184, s[34:35]
	s_mov_b32 m0, s48
	s_nop 0
	global_load_lds_dwordx4 v180, s[34:35]
	s_waitcnt vmcnt(20)
	s_waitcnt lgkmcnt(0)
	s_barrier
; #define PG8_STAGE(bufoff, gbase, voff) do { _Pragma("unroll") for (int _i = 0; _i < 2; ++_i) \
;         __builtin_amdgcn_global_load_lds((const unsigned*)((const char*)(gbase) + (voff)[_i]), (PG8_LAS unsigned*)(lds + (bufoff) + ldsw + _i * 8192), 16, 0, 0); } while (0)
; #define PG8_LDA(dst, b, h) do { _Pragma("unroll") for (int m = 0; m < 4; ++m) _Pragma("unroll") for (int k = 0; k < 2; ++k) dst[m][k] = *(const PG8_LAS bf16x8*)(lds + PG8_SA(b, h) + aoff + m * 2048 + k * 1024); } while (0)
; #define PG8_LDB(dst, b, h) do { _Pragma("unroll") for (int n = 0; n < 2; ++n) _Pragma("unroll") for (int k = 0; k < 2; ++k) dst[n][k] = *(const PG8_LAS bf16x8*)(lds + PG8_SB(b, h) + boff + n * 2048 + k * 1024); } while (0)
; #define PG8_MMA(ai, bj, At, Bt) do { __builtin_amdgcn_s_setprio(1); _Pragma("unroll") for (int m = 0; m < 4; ++m) _Pragma("unroll") for (int n = 0; n < 2; ++n) _Pragma("unroll") for (int k = 0; k < 2; ++k) \
;         acc[ai][bj][m][n] = __builtin_amdgcn_mfma_f32_16x16x32_bf16(Bt[n][k], At[m][k], acc[ai][bj][m][n], 0, 0, 0); __builtin_amdgcn_s_setprio(0); } while (0)
; #define PG8_WAIT_V(n) asm volatile("s_waitcnt vmcnt(" #n ")" ::: "memory")
; #define PG8_WAIT_L(n) asm volatile("s_waitcnt lgkmcnt(" #n ")" ::: "memory")
; #define PG8_BAR __builtin_amdgcn_s_barrier()
; #define PG8_SCHED __builtin_amdgcn_sched_barrier(0)
; template <class Epi, class Sched, bool ALIGN_EPI = false, bool SP2 = false>
; __device__ __forceinline__ void gemm_phase(PG8_LAS unsigned char* lds, const Gemm g, const Sched& S, const Epi& E) {
;     ...
;             PG8_WAIT_V(8); PG8_WAIT_L(0); PG8_BAR; PG8_MMA(1, 0, At, B0); PG8_MMA(1, 1, At, B1); PG8_BAR; PG8_SCHED;
;             PG8_LDB(B0, 1, 0); PG8_LDB(B1, 1, 1); PG8_SCHED; PG8_LDA(At, 1, 0); PG8_STAGE(PG8_SA(0, 1), a2 + hstepA, voffA);
;             PG8_WAIT_V(8); PG8_WAIT_L(0); PG8_BAR; PG8_MMA(0, 0, At, B0); PG8_MMA(0, 1, At, B1); PG8_BAR; PG8_SCHED;
	s_waitcnt lgkmcnt(0)
	v_mfma_f32_16x16x32_bf16 v[58:61], v[130:133], v[162:165], v[58:61]
	v_mfma_f32_16x16x32_bf16 v[54:57], v[138:141], v[162:165], v[54:57]
	v_mfma_f32_16x16x32_bf16 v[42:45], v[130:133], v[170:173], v[42:45]
	v_mfma_f32_16x16x32_bf16 v[38:41], v[138:141], v[170:173], v[38:41]
	v_mfma_f32_16x16x32_bf16 v[26:29], v[130:133], v[196:199], v[26:29]
	v_mfma_f32_16x16x32_bf16 v[22:25], v[138:141], v[196:199], v[22:25]
	v_mfma_f32_16x16x32_bf16 v[10:13], v[130:133], v[212:215], v[10:13]
	v_mfma_f32_16x16x32_bf16 v[6:9], v[138:141], v[212:215], v[6:9]
	v_mfma_f32_16x16x32_bf16 v[58:61], v[134:137], v[166:169], v[58:61]
	v_mfma_f32_16x16x32_bf16 v[54:57], v[142:145], v[166:169], v[54:57]
	v_mfma_f32_16x16x32_bf16 v[42:45], v[134:137], v[174:177], v[42:45]
	v_mfma_f32_16x16x32_bf16 v[38:41], v[142:145], v[174:177], v[38:41]
	v_mfma_f32_16x16x32_bf16 v[26:29], v[134:137], v[208:211], v[26:29]
	v_mfma_f32_16x16x32_bf16 v[22:25], v[142:145], v[208:211], v[22:25]
	v_mfma_f32_16x16x32_bf16 v[10:13], v[134:137], v[216:219], v[10:13]
	v_mfma_f32_16x16x32_bf16 v[6:9], v[142:145], v[216:219], v[6:9]
	v_mfma_f32_16x16x32_bf16 v[62:65], v[146:149], v[162:165], v[62:65]
	v_mfma_f32_16x16x32_bf16 v[50:53], v[154:157], v[162:165], v[50:53]
	v_mfma_f32_16x16x32_bf16 v[46:49], v[146:149], v[170:173], v[46:49]
	v_mfma_f32_16x16x32_bf16 v[34:37], v[154:157], v[170:173], v[34:37]
	v_mfma_f32_16x16x32_bf16 v[30:33], v[146:149], v[196:199], v[30:33]
	v_mfma_f32_16x16x32_bf16 v[18:21], v[154:157], v[196:199], v[18:21]
	v_mfma_f32_16x16x32_bf16 v[14:17], v[146:149], v[212:215], v[14:17]
	v_mfma_f32_16x16x32_bf16 v[2:5], v[154:157], v[212:215], v[2:5]
	v_mfma_f32_16x16x32_bf16 v[62:65], v[150:153], v[166:169], v[62:65]
	v_mfma_f32_16x16x32_bf16 v[50:53], v[158:161], v[166:169], v[50:53]
	v_mfma_f32_16x16x32_bf16 v[46:49], v[150:153], v[174:177], v[46:49]
	v_mfma_f32_16x16x32_bf16 v[34:37], v[158:161], v[174:177], v[34:37]
	v_mfma_f32_16x16x32_bf16 v[30:33], v[150:153], v[208:211], v[30:33]
	v_mfma_f32_16x16x32_bf16 v[18:21], v[158:161], v[208:211], v[18:21]
	v_mfma_f32_16x16x32_bf16 v[14:17], v[150:153], v[216:219], v[14:17]
	v_mfma_f32_16x16x32_bf16 v[2:5], v[158:161], v[216:219], v[2:5]
	s_barrier
	s_add_i32 s73, 0, 0x18000
	s_add_i32 s74, 0, 0x1c000
	v_add_u32_e32 v142, s73, v1
	v_add_u32_e32 v158, s74, v1
	ds_read_b128 v[130:133], v142
	ds_read_b128 v[134:137], v142 offset:1024
	ds_read_b128 v[138:141], v142 offset:2048
	ds_read_b128 v[142:145], v142 offset:3072
	ds_read_b128 v[146:149], v158
	ds_read_b128 v[150:153], v158 offset:1024
	ds_read_b128 v[154:157], v158 offset:2048
	ds_read_b128 v[158:161], v158 offset:3072
	s_add_u32 s34, s34, 0x100000
	s_addc_u32 s35, s35, 0
	s_mov_b32 m0, s49
	ds_read_b128 v[162:165], v207 offset:32768
	ds_read_b128 v[166:169], v207 offset:33792
	ds_read_b128 v[170:173], v207 offset:34816
	ds_read_b128 v[174:177], v207 offset:35840
	ds_read_b128 v[196:199], v207 offset:36864
	ds_read_b128 v[208:211], v207 offset:37888
	ds_read_b128 v[212:215], v207 offset:38912
	ds_read_b128 v[216:219], v207 offset:39936
	global_load_lds_dwordx4 v184, s[34:35]
	s_mov_b32 m0, s60
	s_nop 0
	global_load_lds_dwordx4 v180, s[34:35]
	s_waitcnt vmcnt(20)
	s_waitcnt lgkmcnt(0)
	s_barrier
	s_waitcnt lgkmcnt(0)
	v_mfma_f32_16x16x32_bf16 v[122:125], v[130:133], v[162:165], v[122:125]
	v_mfma_f32_16x16x32_bf16 v[118:121], v[138:141], v[162:165], v[118:121]
	v_mfma_f32_16x16x32_bf16 v[106:109], v[130:133], v[170:173], v[106:109]
	v_mfma_f32_16x16x32_bf16 v[102:105], v[138:141], v[170:173], v[102:105]
	v_mfma_f32_16x16x32_bf16 v[90:93], v[130:133], v[196:199], v[90:93]
	v_mfma_f32_16x16x32_bf16 v[86:89], v[138:141], v[196:199], v[86:89]
	v_mfma_f32_16x16x32_bf16 v[74:77], v[130:133], v[212:215], v[74:77]
	v_mfma_f32_16x16x32_bf16 v[70:73], v[138:141], v[212:215], v[70:73]
	v_mfma_f32_16x16x32_bf16 v[122:125], v[134:137], v[166:169], v[122:125]
	v_mfma_f32_16x16x32_bf16 v[118:121], v[142:145], v[166:169], v[118:121]
	v_mfma_f32_16x16x32_bf16 v[106:109], v[134:137], v[174:177], v[106:109]
	v_mfma_f32_16x16x32_bf16 v[102:105], v[142:145], v[174:177], v[102:105]
	v_mfma_f32_16x16x32_bf16 v[90:93], v[134:137], v[208:211], v[90:93]
	v_mfma_f32_16x16x32_bf16 v[86:89], v[142:145], v[208:211], v[86:89]
	v_mfma_f32_16x16x32_bf16 v[74:77], v[134:137], v[216:219], v[74:77]
	v_mfma_f32_16x16x32_bf16 v[70:73], v[142:145], v[216:219], v[70:73]
	v_mfma_f32_16x16x32_bf16 v[126:129], v[146:149], v[162:165], v[126:129]
	v_mfma_f32_16x16x32_bf16 v[114:117], v[154:157], v[162:165], v[114:117]
	v_mfma_f32_16x16x32_bf16 v[110:113], v[146:149], v[170:173], v[110:113]
	v_mfma_f32_16x16x32_bf16 v[98:101], v[154:157], v[170:173], v[98:101]
	v_mfma_f32_16x16x32_bf16 v[94:97], v[146:149], v[196:199], v[94:97]
	v_mfma_f32_16x16x32_bf16 v[82:85], v[154:157], v[196:199], v[82:85]
	v_mfma_f32_16x16x32_bf16 v[78:81], v[146:149], v[212:215], v[78:81]
	v_mfma_f32_16x16x32_bf16 v[66:69], v[154:157], v[212:215], v[66:69]
	v_mfma_f32_16x16x32_bf16 v[126:129], v[150:153], v[166:169], v[126:129]
	v_mfma_f32_16x16x32_bf16 v[114:117], v[158:161], v[166:169], v[114:117]
	v_mfma_f32_16x16x32_bf16 v[110:113], v[150:153], v[174:177], v[110:113]
	v_mfma_f32_16x16x32_bf16 v[98:101], v[158:161], v[174:177], v[98:101]
	v_mfma_f32_16x16x32_bf16 v[94:97], v[150:153], v[208:211], v[94:97]
	v_mfma_f32_16x16x32_bf16 v[82:85], v[158:161], v[208:211], v[82:85]
	v_mfma_f32_16x16x32_bf16 v[78:81], v[150:153], v[216:219], v[78:81]
	v_mfma_f32_16x16x32_bf16 v[66:69], v[158:161], v[216:219], v[66:69]
	s_barrier
; #define PG8_STAGE(bufoff, gbase, voff) do { _Pragma("unroll") for (int _i = 0; _i < 2; ++_i) \
;         __builtin_amdgcn_global_load_lds((const unsigned*)((const char*)(gbase) + (voff)[_i]), (PG8_LAS unsigned*)(lds + (bufoff) + ldsw + _i * 8192), 16, 0, 0); } while (0)
; #define PG8_LDA(dst, b, h) do { _Pragma("unroll") for (int m = 0; m < 4; ++m) _Pragma("unroll") for (int k = 0; k < 2; ++k) dst[m][k] = *(const PG8_LAS bf16x8*)(lds + PG8_SA(b, h) + aoff + m * 2048 + k * 1024); } while (0)
; #define PG8_MMA(ai, bj, At, Bt) do { __builtin_amdgcn_s_setprio(1); _Pragma("unroll") for (int m = 0; m < 4; ++m) _Pragma("unroll") for (int n = 0; n < 2; ++n) _Pragma("unroll") for (int k = 0; k < 2; ++k) \
;         acc[ai][bj][m][n] = __builtin_amdgcn_mfma_f32_16x16x32_bf16(Bt[n][k], At[m][k], acc[ai][bj][m][n], 0, 0, 0); __builtin_amdgcn_s_setprio(0); } while (0)
; template <class Epi, class Sched, bool ALIGN_EPI = false, bool SP2 = false>
; __device__ __forceinline__ void gemm_phase(PG8_LAS unsigned char* lds, const Gemm g, const Sched& S, const Epi& E) {
;     ...
;             PG8_LDA(At, 1, 1); PG8_STAGE(PG8_SB(1, 0), b3, voffB); PG8_STAGE(PG8_SB(1, 1), b3 + hstepB, voffB); PG8_STAGE(PG8_SA(1, 0), a3, voffA);
;             PG8_WAIT_V(8); PG8_WAIT_L(0); PG8_BAR; PG8_MMA(1, 0, At, B0); PG8_MMA(1, 1, At, B1); PG8_BAR; PG8_SCHED;
;     __device__ __forceinline__ void operator()(const af4 (&acc)[2][2][4][2], const pg8::Unit& u, int wr_, int wc_, int fr_, int fq_) const {
;         const int tid = my_tid(), lane = tid & 63, wid = __builtin_amdgcn_readfirstlane(tid >> 6), wr = wid >> 2, wc = wid & 3, fr = lane & 15, fq = lane >> 4;
;         (void)wr_; (void)wc_; (void)fr_; (void)fq_;
;         const int chbase = u.pn * 128, grp = u.pn / 6;
;         const bf16* wsg = wsb + (size_t)grp * 128 * 128;
;         const int chl = chbase + 32 * wc + 8 * (fr >> 2) + (fr & 3);
;         float lg[2], lb[2];
; #pragma unroll
;         for (int n = 0; n < 2; ++n) { lg[n] = lng[chl + 4 * n]; lb[n] = lnb[chl + 4 * n]; }
;         v4u raw[2][4];
;         auto load_raw = [&](int ai) {
; #pragma unroll
;             for (int ks = 0; ks < 4; ++ks)
; #pragma unroll
;                 for (int n = 0; n < 2; ++n) raw[n][ks] = *(const GAS v4u*)(VT + (size_t)(chl + 4 * n) * MLAT + u.pm * 256 + ai * 128 + 32 * ks + 8 * fq);
;         };
;         load_raw(0);
	s_add_i32 s34, s73, s17
	s_mov_b32 m0, s34
	ds_read_b128 v[162:165], v207 offset:49152
	ds_read_b128 v[166:169], v207 offset:50176
	ds_read_b128 v[170:173], v207 offset:51200
	ds_read_b128 v[174:177], v207 offset:52224
	ds_read_b128 v[196:199], v207 offset:53248
	ds_read_b128 v[208:211], v207 offset:54272
	ds_read_b128 v[212:215], v207 offset:55296
	ds_read_b128 v[216:219], v207 offset:56320
	global_load_lds_dwordx4 v182, s[98:99]
	s_add_i32 m0, s34, 0x2000
	s_add_u32 s34, s42, 0x100080
	s_addc_u32 s35, s43, 0
	s_add_i32 s42, s74, s17
	global_load_lds_dwordx4 v178, s[98:99]
	s_mov_b32 m0, s42
	s_nop 0
	global_load_lds_dwordx4 v182, s[34:35]
	s_add_i32 m0, s42, 0x2000
	s_nop 0
	global_load_lds_dwordx4 v178, s[34:35]
	s_mov_b32 m0, s64
	s_nop 0
	global_load_lds_dwordx4 v184, s[100:101]
	s_mov_b32 m0, s65
	s_nop 0
	global_load_lds_dwordx4 v180, s[100:101]
	s_waitcnt vmcnt(8)
	s_waitcnt lgkmcnt(0)
	s_barrier
	s_waitcnt lgkmcnt(0)
	v_mfma_f32_16x16x32_bf16 v[58:61], v[130:133], v[162:165], v[58:61]
	v_mfma_f32_16x16x32_bf16 v[54:57], v[138:141], v[162:165], v[54:57]
	v_mfma_f32_16x16x32_bf16 v[42:45], v[130:133], v[170:173], v[42:45]
	v_mfma_f32_16x16x32_bf16 v[38:41], v[138:141], v[170:173], v[38:41]
	v_mfma_f32_16x16x32_bf16 v[26:29], v[130:133], v[196:199], v[26:29]
	v_mfma_f32_16x16x32_bf16 v[22:25], v[138:141], v[196:199], v[22:25]
	v_mfma_f32_16x16x32_bf16 v[10:13], v[130:133], v[212:215], v[10:13]
	v_mfma_f32_16x16x32_bf16 v[6:9], v[138:141], v[212:215], v[6:9]
	v_mfma_f32_16x16x32_bf16 v[58:61], v[134:137], v[166:169], v[58:61]
	v_mfma_f32_16x16x32_bf16 v[54:57], v[142:145], v[166:169], v[54:57]
	v_mfma_f32_16x16x32_bf16 v[42:45], v[134:137], v[174:177], v[42:45]
	v_mfma_f32_16x16x32_bf16 v[38:41], v[142:145], v[174:177], v[38:41]
	v_mfma_f32_16x16x32_bf16 v[26:29], v[134:137], v[208:211], v[26:29]
	v_mfma_f32_16x16x32_bf16 v[22:25], v[142:145], v[208:211], v[22:25]
	v_mfma_f32_16x16x32_bf16 v[10:13], v[134:137], v[216:219], v[10:13]
	v_mfma_f32_16x16x32_bf16 v[6:9], v[142:145], v[216:219], v[6:9]
	v_mfma_f32_16x16x32_bf16 v[62:65], v[146:149], v[162:165], v[62:65]
	v_mfma_f32_16x16x32_bf16 v[50:53], v[154:157], v[162:165], v[50:53]
	v_mfma_f32_16x16x32_bf16 v[46:49], v[146:149], v[170:173], v[46:49]
	v_mfma_f32_16x16x32_bf16 v[34:37], v[154:157], v[170:173], v[34:37]
	v_mfma_f32_16x16x32_bf16 v[30:33], v[146:149], v[196:199], v[30:33]
	v_mfma_f32_16x16x32_bf16 v[18:21], v[154:157], v[196:199], v[18:21]
	v_mfma_f32_16x16x32_bf16 v[14:17], v[146:149], v[212:215], v[14:17]
	v_mfma_f32_16x16x32_bf16 v[2:5], v[154:157], v[212:215], v[2:5]
	v_mfma_f32_16x16x32_bf16 v[62:65], v[150:153], v[166:169], v[62:65]
	v_mfma_f32_16x16x32_bf16 v[50:53], v[158:161], v[166:169], v[50:53]
	v_mfma_f32_16x16x32_bf16 v[46:49], v[150:153], v[174:177], v[46:49]
	v_mfma_f32_16x16x32_bf16 v[34:37], v[158:161], v[174:177], v[34:37]
	v_mfma_f32_16x16x32_bf16 v[30:33], v[150:153], v[208:211], v[30:33]
	v_mfma_f32_16x16x32_bf16 v[18:21], v[158:161], v[208:211], v[18:21]
	v_mfma_f32_16x16x32_bf16 v[14:17], v[150:153], v[216:219], v[14:17]
	v_mfma_f32_16x16x32_bf16 v[2:5], v[158:161], v[216:219], v[2:5]
	s_barrier
	s_add_i32 s53, s53, 2
	s_add_u32 s40, s40, 0x100
	s_addc_u32 s41, s41, 0
	s_add_u32 s45, s45, 0x100
	s_addc_u32 s52, s52, 0
	s_setprio 0
	s_and_b64 vcc, exec, s[14:15]
	s_cbranch_vccz .LBB0_1130
	s_barrier
.LBB0_1130:
	s_lshl_b32 s98, s6, 11
	s_sub_i32 s98, 0x20000, s98
	v_readfirstlane_b32 s99, v0
	s_nop 1
	s_cmpk_gt_u32 s99, 0x7f
	s_cbranch_scc1 .Lp11_st_nowr
	v_lshlrev_b32_e32 v200, 4, v0
	v_add_u32_e32 v200, 0x20000, v200
	ds_write_b128 v200, v[230:233]
.Lp11_st_nowr:
	s_waitcnt lgkmcnt(0)
	s_barrier
	v_mov_b32_e32 v164, v0
	s_mul_hi_i32 s23, s44, 0x2aaaaaab
	s_lshr_b32 s26, s23, 31
	v_readfirstlane_b32 s25, v164
	v_lshlrev_b32_e32 v130, 1, v164
	s_lshl_b32 s40, s44, 7
	s_add_i32 s44, s23, s26
	s_lshr_b32 s23, s25, 1
	v_and_b32_e32 v130, 24, v130
	v_and_b32_e32 v131, 3, v164
	s_ashr_i32 s45, s44, 31
	s_and_b32 s23, s23, 0x60
	v_or3_b32 v130, v131, v130, s40
	s_lshl_b64 s[26:27], s[44:45], 15
	v_or_b32_e32 v146, s23, v130
	v_or_b32_e32 v134, 4, v146
	s_add_u32 s52, s62, s26
	v_ashrrev_i32_e32 v147, 31, v146
	v_ashrrev_i32_e32 v135, 31, v134
	s_addc_u32 s53, s63, s27
	s_lshl_b32 s42, s6, 8
	v_lshrrev_b32_e32 v132, 1, v164
	v_lshlrev_b64 v[130:131], 15, v[146:147]
	s_ashr_i32 s43, s42, 31
	v_and_b32_e32 v209, 24, v132
	v_lshlrev_b64 v[134:135], 15, v[134:135]
	v_lshl_add_u64 v[130:131], s[50:51], 0, v[130:131]
	s_lshl_b64 s[26:27], s[42:43], 1
	v_lshl_add_u64 v[134:135], s[50:51], 0, v[134:135]
	v_or_b32_e32 v162, s42, v209
	v_lshl_add_u64 v[130:131], v[130:131], 0, s[26:27]
	v_lshlrev_b32_e32 v186, 1, v209
	v_lshl_add_u64 v[148:149], v[134:135], 0, s[26:27]
	v_ashrrev_i32_e32 v163, 31, v162
	v_lshl_add_u64 v[216:217], v[130:131], 0, v[186:187]
	v_lshl_add_u32 v150, v162, 3, s98
	v_lshl_add_u64 v[220:221], v[148:149], 0, v[186:187]
	v_mov_b64_e32 v[130:131], v[192:193]
	v_mov_b64_e32 v[132:133], v[194:195]
	ds_read_b128 v[134:137], v150 offset:16
	ds_read_b128 v[138:141], v150
	ds_read_b128 v[142:145], v150 offset:48
	ds_read_b128 v[166:169], v150 offset:32
	v_mov_b64_e32 v[170:171], v[222:223]
	v_mov_b64_e32 v[172:173], v[224:225]
	v_readlane_b32 s80, v254, 2
	v_readlane_b32 s81, v254, 3
	v_readlane_b32 s90, v254, 12
	v_readlane_b32 s91, v254, 13
	v_readlane_b32 s92, v254, 14
	v_readlane_b32 s93, v254, 15
	v_lshlrev_b64 v[146:147], 2, v[146:147]
	s_mov_b64 s[78:79], s[90:91]
	s_mov_b64 s[80:81], s[92:93]
	v_lshl_add_u64 v[148:149], s[78:79], 0, v[146:147]
	v_lshl_add_u64 v[146:147], s[80:81], 0, v[146:147]
	v_mov_b32_e32 v206, v183
	v_mov_b32_e32 v208, v179
; #define GAS __attribute__((address_space(1)))
; __device__ __forceinline__ void unpack8(const v4u w, float (&f)[8]) { f[0] = bflo(w.x); f[1] = bfhi(w.x); f[2] = bflo(w.y); f[3] = bfhi(w.y); f[4] = bflo(w.z); f[5] = bfhi(w.z); f[6] = bflo(w.w); f[7] = bfhi(w.w); }
; __device__ __forceinline__ v4u pack8(const float (&f)[8]) { v4u w; w.x = pk2(f[0], f[1]); w.y = pk2(f[2], f[3]); w.z = pk2(f[4], f[5]); w.w = pk2(f[6], f[7]); return w; }
;     __device__ __forceinline__ void operator()(const af4 (&acc)[2][2][4][2], const pg8::Unit& u, int wr_, int wc_, int fr_, int fq_) const {
;     ...
;         for (int n = 0; n < 2; ++n) { lg[n] = lng[chl + 4 * n]; lb[n] = lnb[chl + 4 * n]; }
;         v4u raw[2][4];
;         auto load_raw = [&](int ai) {
; #pragma unroll
;             for (int ks = 0; ks < 4; ++ks)
; #pragma unroll
;                 for (int n = 0; n < 2; ++n) raw[n][ks] = *(const GAS v4u*)(VT + (size_t)(chl + 4 * n) * MLAT + u.pm * 256 + ai * 128 + 32 * ks + 8 * fq);
;         };
;         load_raw(0);
; #pragma unroll
;         for (int ai = 0; ai < 2; ++ai) {
;             const int tok0 = u.pm * 256 + ai * 128;
;             bf16x8 av[2][4];
; #pragma unroll
;             for (int ks = 0; ks < 4; ++ks) {
;                 const int j0 = tok0 + 32 * ks + 8 * fq;
;                 f32x4 st[4];
; #pragma unroll
;                 for (int q = 0; q < 4; ++q) st[q] = *(const GAS f32x4*)(stats + (size_t)(j0 + 2 * q) * 2);
; #pragma unroll
;                 for (int n = 0; n < 2; ++n) {
;                     float vf[8];
;                     unpack8(raw[n][ks], vf);
; #pragma unroll
;                     for (int q = 0; q < 4; ++q) { f32x2 t = {vf[2 * q], vf[2 * q + 1]}; t = t * (f32x2){st[q].z, st[q].w} + (f32x2){st[q].x, st[q].y}; t = t * lg[n] + lb[n]; vf[2 * q] = t.x; vf[2 * q + 1] = t.y; }
;                     av[n][ks] = __builtin_bit_cast(bf16x8, pack8(vf));
	v_mov_b32_e32 v202, v181
	v_mov_b32_e32 v204, v185
	v_mov_b64_e32 v[174:175], v[226:227]
	v_mov_b64_e32 v[176:177], v[228:229]
	v_mov_b64_e32 v[150:151], v[234:235]
	v_mov_b64_e32 v[152:153], v[236:237]
	v_mov_b64_e32 v[158:159], v[238:239]
	v_mov_b64_e32 v[160:161], v[240:241]
	v_mov_b64_e32 v[196:197], v[242:243]
	v_mov_b64_e32 v[198:199], v[244:245]
	s_nop 0
	v_mov_b64_e32 v[146:147], v[246:247]
	v_mov_b64_e32 v[148:149], v[248:249]
	v_mov_b64_e32 v[154:155], v[250:251]
	v_mov_b64_e32 v[156:157], v[252:253]
	s_ashr_i32 s6, s25, 2
	s_andn2_b32 s6, s6, 63
	v_pk_mul_f32 v[226:227], v[126:127], s[20:21] op_sel_hi:[1,0]
	v_pk_mul_f32 v[234:235], v[122:123], v[126:127]
	v_pk_mul_f32 v[126:127], v[128:129], s[20:21] op_sel_hi:[1,0]
	v_pk_mul_f32 v[236:237], v[124:125], v[128:129]
	v_pk_mul_f32 v[128:129], v[120:121], v[120:121]
	v_pk_mul_f32 v[228:229], v[118:119], v[118:119]
	v_pk_mul_f32 v[230:231], v[114:115], s[20:21] op_sel_hi:[1,0]
	v_pk_mul_f32 v[238:239], v[118:119], v[114:115]
	v_pk_mul_f32 v[114:115], v[116:117], s[20:21] op_sel_hi:[1,0]
	v_pk_mul_f32 v[240:241], v[120:121], v[116:117]
	v_exp_f32_e32 v126, v126
	v_exp_f32_e32 v127, v127
	v_exp_f32_e32 v114, v114
	v_exp_f32_e32 v115, v115
	s_ashr_i32 s41, s40, 31
	v_pk_add_f32 v[126:127], v[126:127], 1.0 op_sel_hi:[1,0]
	s_lshl_b64 s[40:41], s[40:41], 1
	v_pk_add_f32 v[114:115], v[114:115], 1.0 op_sel_hi:[1,0]
	v_pk_mul_f32 v[252:253], v[102:103], v[98:99]
	v_pk_mul_f32 v[192:193], v[104:105], v[100:101]
	s_andn2_b64 vcc, exec, s[4:5]
	v_readlane_b32 s82, v254, 4
	v_readlane_b32 s83, v254, 5
	v_readlane_b32 s84, v254, 6
	v_readlane_b32 s85, v254, 7
	v_readlane_b32 s86, v254, 8
	v_readlane_b32 s87, v254, 9
	v_readlane_b32 s88, v254, 10
	v_readlane_b32 s89, v254, 11
	v_readlane_b32 s94, v254, 16
	v_readlane_b32 s95, v254, 17
	s_waitcnt vmcnt(0)
	s_waitcnt lgkmcnt(0)
	v_lshlrev_b32_e32 v200, 16, v130
	v_and_b32_e32 v201, 0xffff0000, v130
	v_lshlrev_b32_e32 v212, 16, v170
	v_and_b32_e32 v213, 0xffff0000, v170
	v_lshlrev_b32_e32 v130, 16, v131
	v_and_b32_e32 v131, 0xffff0000, v131
	v_lshlrev_b32_e32 v210, 16, v132
	v_and_b32_e32 v211, 0xffff0000, v132
	v_lshlrev_b32_e32 v132, 16, v133
	v_and_b32_e32 v133, 0xffff0000, v133
	v_pk_fma_f32 v[200:201], v[140:141], v[200:201], v[138:139]
	v_lshlrev_b32_e32 v170, 16, v171
	v_and_b32_e32 v171, 0xffff0000, v171
	v_pk_fma_f32 v[138:139], v[140:141], v[212:213], v[138:139]
	v_pk_fma_f32 v[130:131], v[136:137], v[130:131], v[134:135]
	v_pk_fma_f32 v[210:211], v[168:169], v[210:211], v[166:167]
	v_pk_fma_f32 v[132:133], v[144:145], v[132:133], v[142:143]
	v_lshlrev_b32_e32 v214, 16, v172
	v_and_b32_e32 v215, 0xffff0000, v172
	v_lshlrev_b32_e32 v172, 16, v173
	v_and_b32_e32 v173, 0xffff0000, v173
	v_pk_fma_f32 v[134:135], v[136:137], v[170:171], v[134:135]
	v_pk_fma_f32 v[138:139], v[202:203], v[138:139], v[204:205] op_sel_hi:[0,1,0]
	v_pk_fma_f32 v[200:201], v[208:209], v[200:201], v[206:207] op_sel_hi:[0,1,0]
	v_pk_fma_f32 v[218:219], v[208:209], v[130:131], v[206:207] op_sel_hi:[0,1,0]
	v_pk_fma_f32 v[210:211], v[208:209], v[210:211], v[206:207] op_sel_hi:[0,1,0]
	v_pk_fma_f32 v[222:223], v[208:209], v[132:133], v[206:207] op_sel_hi:[0,1,0]
	v_pk_fma_f32 v[140:141], v[144:145], v[172:173], v[142:143]
	v_cvt_pk_bf16_f32 v130, v200, v201
	v_cvt_pk_bf16_f32 v131, v218, v219
	v_cvt_pk_bf16_f32 v132, v210, v211
	v_cvt_pk_bf16_f32 v133, v222, v223
	v_pk_fma_f32 v[142:143], v[202:203], v[134:135], v[204:205] op_sel_hi:[0,1,0]
	v_cvt_pk_bf16_f32 v134, v138, v139
	v_or_b32_e32 v138, 32, v162
	v_pk_fma_f32 v[136:137], v[168:169], v[214:215], v[166:167]
	v_ashrrev_i32_e32 v139, 31, v138
	v_pk_fma_f32 v[136:137], v[202:203], v[136:137], v[204:205] op_sel_hi:[0,1,0]
	v_pk_fma_f32 v[140:141], v[202:203], v[140:141], v[204:205] op_sel_hi:[0,1,0]
	v_lshl_add_u32 v170, v138, 3, s98
	v_cvt_pk_bf16_f32 v135, v142, v143
	v_cvt_pk_bf16_f32 v136, v136, v137
	v_cvt_pk_bf16_f32 v137, v140, v141
	ds_read_b128 v[138:141], v170
	ds_read_b128 v[142:145], v170 offset:16
	ds_read_b128 v[166:169], v170 offset:32
	s_nop 0
	ds_read_b128 v[170:173], v170 offset:48
	v_or_b32_e32 v200, 64, v162
	v_lshlrev_b32_e32 v210, 16, v174
	v_and_b32_e32 v211, 0xffff0000, v174
	v_lshlrev_b32_e32 v174, 16, v175
	v_and_b32_e32 v175, 0xffff0000, v175
	v_lshlrev_b32_e32 v212, 16, v176
	v_and_b32_e32 v213, 0xffff0000, v176
	v_lshlrev_b32_e32 v176, 16, v177
	v_and_b32_e32 v177, 0xffff0000, v177
	v_lshlrev_b32_e32 v214, 16, v196
	v_and_b32_e32 v215, 0xffff0000, v196
	v_lshlrev_b32_e32 v196, 16, v197
	v_and_b32_e32 v197, 0xffff0000, v197
	v_lshlrev_b32_e32 v218, 16, v198
	v_and_b32_e32 v219, 0xffff0000, v198
	v_lshlrev_b32_e32 v198, 16, v199
	v_and_b32_e32 v199, 0xffff0000, v199
	v_ashrrev_i32_e32 v201, 31, v200
	v_lshl_add_u32 v200, v200, 3, s98
	v_or_b32_e32 v162, 0x60, v162
	v_ashrrev_i32_e32 v163, 31, v162
	v_lshl_add_u32 v162, v162, 3, s98
	v_and_b32_e32 v165, 0xffff0000, v160
	s_waitcnt lgkmcnt(3)
	v_pk_fma_f32 v[210:211], v[140:141], v[210:211], v[138:139]
	s_waitcnt lgkmcnt(2)
	v_pk_fma_f32 v[174:175], v[144:145], v[174:175], v[142:143]
	s_waitcnt lgkmcnt(1)
	v_pk_fma_f32 v[212:213], v[168:169], v[212:213], v[166:167]
	s_waitcnt lgkmcnt(0)
; #define GAS __attribute__((address_space(1)))
; __device__ __forceinline__ void unpack8(const v4u w, float (&f)[8]) { f[0] = bflo(w.x); f[1] = bfhi(w.x); f[2] = bflo(w.y); f[3] = bfhi(w.y); f[4] = bflo(w.z); f[5] = bfhi(w.z); f[6] = bflo(w.w); f[7] = bfhi(w.w); }
; __device__ __forceinline__ v4u pack8(const float (&f)[8]) { v4u w; w.x = pk2(f[0], f[1]); w.y = pk2(f[2], f[3]); w.z = pk2(f[4], f[5]); w.w = pk2(f[6], f[7]); return w; }
;     __device__ __forceinline__ void operator()(const af4 (&acc)[2][2][4][2], const pg8::Unit& u, int wr_, int wc_, int fr_, int fq_) const {
;     ...
;             for (int ks = 0; ks < 4; ++ks) {
;                 const int j0 = tok0 + 32 * ks + 8 * fq;
;                 f32x4 st[4];
; #pragma unroll
;                 for (int q = 0; q < 4; ++q) st[q] = *(const GAS f32x4*)(stats + (size_t)(j0 + 2 * q) * 2);
; #pragma unroll
;                 for (int n = 0; n < 2; ++n) {
;                     float vf[8];
;                     unpack8(raw[n][ks], vf);
; #pragma unroll
;                     for (int q = 0; q < 4; ++q) { f32x2 t = {vf[2 * q], vf[2 * q + 1]}; t = t * (f32x2){st[q].z, st[q].w} + (f32x2){st[q].x, st[q].y}; t = t * lg[n] + lb[n]; vf[2 * q] = t.x; vf[2 * q + 1] = t.y; }
;                     av[n][ks] = __builtin_bit_cast(bf16x8, pack8(vf));
;                 }
;             }
; #pragma unroll
;             for (int m = 0; m < 4; ++m) {
;                 if (ai == 0 && m == 0) load_raw(1);
;                 const int it = wr * 64 + m * 16 + fr;
;                 bf16x8 wf[4];
; #pragma unroll
;                 for (int ks = 0; ks < 4; ++ks) wf[ks] = *(const GAS bf16x8*)(wsg + (size_t)it * 128 + 32 * ks + 8 * fq);
;                 const float bsi = bs[grp * 128 + it];
	v_pk_fma_f32 v[176:177], v[172:173], v[176:177], v[170:171]
	v_pk_fma_f32 v[138:139], v[140:141], v[214:215], v[138:139]
	v_pk_fma_f32 v[140:141], v[144:145], v[196:197], v[142:143]
	v_pk_fma_f32 v[142:143], v[168:169], v[218:219], v[166:167]
	v_pk_fma_f32 v[144:145], v[172:173], v[198:199], v[170:171]
	v_pk_fma_f32 v[166:167], v[208:209], v[210:211], v[206:207] op_sel_hi:[0,1,0]
	v_pk_fma_f32 v[168:169], v[208:209], v[174:175], v[206:207] op_sel_hi:[0,1,0]
	v_pk_fma_f32 v[170:171], v[208:209], v[212:213], v[206:207] op_sel_hi:[0,1,0]
	v_pk_fma_f32 v[172:173], v[208:209], v[176:177], v[206:207] op_sel_hi:[0,1,0]
	v_pk_fma_f32 v[138:139], v[202:203], v[138:139], v[204:205] op_sel_hi:[0,1,0]
	v_pk_fma_f32 v[140:141], v[202:203], v[140:141], v[204:205] op_sel_hi:[0,1,0]
	v_pk_fma_f32 v[174:175], v[202:203], v[142:143], v[204:205] op_sel_hi:[0,1,0]
	v_pk_fma_f32 v[176:177], v[202:203], v[144:145], v[204:205] op_sel_hi:[0,1,0]
	v_cvt_pk_bf16_f32 v142, v166, v167
	v_cvt_pk_bf16_f32 v143, v168, v169
	v_cvt_pk_bf16_f32 v144, v170, v171
	v_cvt_pk_bf16_f32 v145, v172, v173
	v_cvt_pk_bf16_f32 v138, v138, v139
	v_cvt_pk_bf16_f32 v139, v140, v141
	v_cvt_pk_bf16_f32 v140, v174, v175
	v_cvt_pk_bf16_f32 v141, v176, v177
	ds_read_b128 v[166:169], v200
	ds_read_b128 v[170:173], v200 offset:16
	ds_read_b128 v[174:177], v200 offset:32
	ds_read_b128 v[196:199], v200 offset:48
	v_lshlrev_b32_e32 v200, 16, v150
	v_and_b32_e32 v201, 0xffff0000, v150
	v_lshlrev_b32_e32 v150, 16, v151
	v_and_b32_e32 v151, 0xffff0000, v151
	v_lshlrev_b32_e32 v210, 16, v152
	v_and_b32_e32 v211, 0xffff0000, v152
	v_lshlrev_b32_e32 v152, 16, v153
	v_and_b32_e32 v153, 0xffff0000, v153
	v_lshlrev_b32_e32 v212, 16, v146
	v_and_b32_e32 v213, 0xffff0000, v146
	v_lshlrev_b32_e32 v146, 16, v147
	v_and_b32_e32 v147, 0xffff0000, v147
	v_lshlrev_b32_e32 v214, 16, v148
	v_and_b32_e32 v215, 0xffff0000, v148
	v_lshlrev_b32_e32 v148, 16, v149
	v_and_b32_e32 v149, 0xffff0000, v149
	v_lshl_add_u64 v[218:219], s[52:53], 0, v[186:187]
	s_waitcnt lgkmcnt(3)
	v_pk_fma_f32 v[200:201], v[168:169], v[200:201], v[166:167]
	s_waitcnt lgkmcnt(2)
	v_pk_fma_f32 v[150:151], v[172:173], v[150:151], v[170:171]
	s_waitcnt lgkmcnt(1)
	v_pk_fma_f32 v[210:211], v[176:177], v[210:211], v[174:175]
	s_waitcnt lgkmcnt(0)
	v_pk_fma_f32 v[152:153], v[198:199], v[152:153], v[196:197]
	v_pk_fma_f32 v[166:167], v[168:169], v[212:213], v[166:167]
	v_pk_fma_f32 v[146:147], v[172:173], v[146:147], v[170:171]
	v_pk_fma_f32 v[168:169], v[176:177], v[214:215], v[174:175]
	v_pk_fma_f32 v[148:149], v[198:199], v[148:149], v[196:197]
	v_pk_fma_f32 v[170:171], v[208:209], v[200:201], v[206:207] op_sel_hi:[0,1,0]
	v_pk_fma_f32 v[172:173], v[208:209], v[150:151], v[206:207] op_sel_hi:[0,1,0]
	v_pk_fma_f32 v[174:175], v[208:209], v[210:211], v[206:207] op_sel_hi:[0,1,0]
	v_pk_fma_f32 v[176:177], v[208:209], v[152:153], v[206:207] op_sel_hi:[0,1,0]
	v_pk_fma_f32 v[166:167], v[202:203], v[166:167], v[204:205] op_sel_hi:[0,1,0]
	v_pk_fma_f32 v[196:197], v[202:203], v[146:147], v[204:205] op_sel_hi:[0,1,0]
	v_pk_fma_f32 v[168:169], v[202:203], v[168:169], v[204:205] op_sel_hi:[0,1,0]
	v_pk_fma_f32 v[198:199], v[202:203], v[148:149], v[204:205] op_sel_hi:[0,1,0]
	v_cvt_pk_bf16_f32 v150, v170, v171
	v_cvt_pk_bf16_f32 v151, v172, v173
	v_cvt_pk_bf16_f32 v152, v174, v175
	v_cvt_pk_bf16_f32 v153, v176, v177
	v_cvt_pk_bf16_f32 v146, v166, v167
	v_cvt_pk_bf16_f32 v147, v196, v197
	v_cvt_pk_bf16_f32 v148, v168, v169
	v_cvt_pk_bf16_f32 v149, v198, v199
	ds_read_b128 v[166:169], v162
	ds_read_b128 v[170:173], v162 offset:16
	ds_read_b128 v[174:177], v162 offset:32
	ds_read_b128 v[196:199], v162 offset:48
	v_and_or_b32 v210, v164, 15, s6
	v_lshl_add_u32 v162, s44, 7, v210
	v_ashrrev_i32_e32 v163, 31, v162
	v_lshl_add_u64 v[200:201], v[162:163], 2, s[76:77]
	v_lshlrev_b32_e32 v162, 16, v158
	v_and_b32_e32 v163, 0xffff0000, v158
	v_lshlrev_b32_e32 v164, 16, v160
	v_lshlrev_b32_e32 v212, 16, v154
	v_and_b32_e32 v213, 0xffff0000, v154
	v_lshlrev_b32_e32 v154, 16, v155
	v_and_b32_e32 v155, 0xffff0000, v155
	v_lshlrev_b32_e32 v158, 16, v159
	v_and_b32_e32 v159, 0xffff0000, v159
	v_lshlrev_b32_e32 v160, 16, v161
	v_and_b32_e32 v161, 0xffff0000, v161
	v_lshlrev_b32_e32 v214, 16, v156
	v_and_b32_e32 v215, 0xffff0000, v156
	v_lshlrev_b32_e32 v156, 16, v157
	v_and_b32_e32 v157, 0xffff0000, v157
	v_ashrrev_i32_e32 v211, 31, v210
	s_lshl_b32 s6, s23, 1
	s_or_b32 s23, s42, 0x80
	s_waitcnt lgkmcnt(3)
	v_pk_fma_f32 v[162:163], v[168:169], v[162:163], v[166:167]
	s_waitcnt lgkmcnt(2)
	v_pk_fma_f32 v[154:155], v[172:173], v[154:155], v[170:171]
	s_waitcnt lgkmcnt(1)
	v_pk_fma_f32 v[164:165], v[176:177], v[164:165], v[174:175]
	v_pk_fma_f32 v[158:159], v[172:173], v[158:159], v[170:171]
	s_waitcnt lgkmcnt(0)
; #define GAS __attribute__((address_space(1)))
; __device__ __forceinline__ v4u pack8(const float (&f)[8]) { v4u w; w.x = pk2(f[0], f[1]); w.y = pk2(f[2], f[3]); w.z = pk2(f[4], f[5]); w.w = pk2(f[6], f[7]); return w; }
; __device__ __forceinline__ float fexp2(float x) { return __builtin_amdgcn_exp2f(x); }
; __device__ __forceinline__ float frcp(float x) { return __builtin_amdgcn_rcpf(x); }
;     __device__ __forceinline__ void operator()(const af4 (&acc)[2][2][4][2], const pg8::Unit& u, int wr_, int wc_, int fr_, int fq_) const {
;     ...
;             for (int m = 0; m < 4; ++m) {
;                 if (ai == 0 && m == 0) load_raw(1);
;                 const int it = wr * 64 + m * 16 + fr;
;                 bf16x8 wf[4];
; #pragma unroll
;                 for (int ks = 0; ks < 4; ++ks) wf[ks] = *(const GAS bf16x8*)(wsg + (size_t)it * 128 + 32 * ks + 8 * fq);
;                 const float bsi = bs[grp * 128 + it];
;                 af4 vm[2] = {(af4){bsi, bsi, bsi, bsi}, (af4){bsi, bsi, bsi, bsi}};
; #pragma unroll
;                 for (int ks = 0; ks < 4; ++ks) {
; #pragma unroll
;                     for (int n = 0; n < 2; ++n) vm[n] = __builtin_amdgcn_mfma_f32_16x16x32_bf16(av[n][ks], wf[ks], vm[n], 0, 0, 0);
;                 }
;                 float o[8];
; #pragma unroll
;                 for (int n = 0; n < 2; ++n)
; #pragma unroll
;                     for (int e = 0; e < 4; e += 2) {
;                         const f32x2 uu = {acc[ai][0][m][n][e], acc[ai][0][m][n][e + 1]}, gg = {acc[ai][1][m][n][e], acc[ai][1][m][n][e + 1]}, vv = {vm[n][e], vm[n][e + 1]};
;                         const f32x2 ar = uu * (uu * uu * (-2.302208198f * 0.044715f) + (-2.302208198f));
;                         const f32x2 gs = gg * (-1.4426950408889634f);
;                         const f32x2 ea = {fexp2(ar.x), fexp2(ar.y)}, eb = {fexp2(gs.x), fexp2(gs.y)};
;                         const f32x2 q = eb + 1.0f, den = ea * q + q;
;                         const f32x2 r = {frcp(den.x), frcp(den.y)};
;                         const f32x2 w = (uu * gg) * vv * r;
;                         o[4 * n + e] = w.x; o[4 * n + e + 1] = w.y; }
;                 *(GAS v4u*)(Y + (size_t)(tok0 + it) * CW + chbase + 32 * wc + 8 * fq) = pack8(o);
	v_pk_fma_f32 v[160:161], v[198:199], v[160:161], v[196:197]
	v_pk_fma_f32 v[166:167], v[168:169], v[212:213], v[166:167]
	v_pk_fma_f32 v[168:169], v[176:177], v[214:215], v[174:175]
	v_pk_fma_f32 v[156:157], v[198:199], v[156:157], v[196:197]
	v_pk_fma_f32 v[162:163], v[208:209], v[162:163], v[206:207] op_sel_hi:[0,1,0]
	v_pk_fma_f32 v[164:165], v[208:209], v[164:165], v[206:207] op_sel_hi:[0,1,0]
	v_pk_fma_f32 v[154:155], v[202:203], v[154:155], v[204:205] op_sel_hi:[0,1,0]
	v_pk_fma_f32 v[158:159], v[208:209], v[158:159], v[206:207] op_sel_hi:[0,1,0]
	v_pk_fma_f32 v[160:161], v[208:209], v[160:161], v[206:207] op_sel_hi:[0,1,0]
	v_pk_fma_f32 v[170:171], v[202:203], v[166:167], v[204:205] op_sel_hi:[0,1,0]
	v_pk_fma_f32 v[172:173], v[202:203], v[168:169], v[204:205] op_sel_hi:[0,1,0]
	v_pk_fma_f32 v[156:157], v[202:203], v[156:157], v[204:205] op_sel_hi:[0,1,0]
	v_cvt_pk_bf16_f32 v166, v162, v163
	v_cvt_pk_bf16_f32 v167, v158, v159
	v_cvt_pk_bf16_f32 v168, v164, v165
	v_cvt_pk_bf16_f32 v169, v160, v161
	v_cvt_pk_bf16_f32 v162, v170, v171
	v_cvt_pk_bf16_f32 v163, v154, v155
	v_cvt_pk_bf16_f32 v164, v172, v173
	v_cvt_pk_bf16_f32 v165, v156, v157
	global_load_dword v154, v[200:201], off
	v_lshlrev_b64 v[156:157], 8, v[210:211]
	v_lshl_add_u64 v[214:215], v[218:219], 0, v[156:157]
	global_load_dwordx4 v[158:161], v[214:215], off
	global_load_dwordx4 v[170:173], v[214:215], off offset:64
	global_load_dwordx4 v[174:177], v[214:215], off offset:128
	global_load_dwordx4 v[222:225], v[214:215], off offset:192
	v_pk_mul_f32 v[156:157], v[124:125], v[124:125]
	v_pk_mul_f32 v[212:213], v[122:123], v[122:123]
	v_mov_b64_e32 v[196:197], s[18:19]
	v_pk_fma_f32 v[116:117], v[212:213], s[16:17], v[196:197] op_sel_hi:[1,0,0] neg_lo:[1,0,0] neg_hi:[1,0,0]
	v_exp_f32_e32 v212, v226
	v_exp_f32_e32 v213, v227
	v_pk_fma_f32 v[156:157], v[156:157], s[16:17], v[196:197] op_sel_hi:[1,0,0] neg_lo:[1,0,0] neg_hi:[1,0,0]
	v_pk_fma_f32 v[226:227], v[228:229], s[16:17], v[196:197] op_sel_hi:[1,0,0] neg_lo:[1,0,0] neg_hi:[1,0,0]
	v_pk_fma_f32 v[128:129], v[128:129], s[16:17], v[196:197] op_sel_hi:[1,0,0] neg_lo:[1,0,0] neg_hi:[1,0,0]
	v_exp_f32_e32 v228, v230
	v_exp_f32_e32 v229, v231
	v_pk_mul_f32 v[116:117], v[122:123], v[116:117]
	v_pk_mul_f32 v[122:123], v[124:125], v[156:157]
	v_pk_mul_f32 v[118:119], v[118:119], v[226:227]
	v_pk_mul_f32 v[120:121], v[120:121], v[128:129]
	v_exp_f32_e32 v116, v116
	v_exp_f32_e32 v117, v117
	v_exp_f32_e32 v122, v122
	v_exp_f32_e32 v123, v123
	v_exp_f32_e32 v118, v118
	v_exp_f32_e32 v119, v119
	v_exp_f32_e32 v120, v120
	v_exp_f32_e32 v121, v121
	v_pk_add_f32 v[124:125], v[212:213], 1.0 op_sel_hi:[1,0]
	v_pk_add_f32 v[128:129], v[228:229], 1.0 op_sel_hi:[1,0]
	v_pk_fma_f32 v[124:125], v[116:117], v[124:125], v[124:125]
	v_pk_fma_f32 v[122:123], v[122:123], v[126:127], v[126:127]
	v_pk_fma_f32 v[126:127], v[118:119], v[128:129], v[128:129]
	v_pk_fma_f32 v[128:129], v[120:121], v[114:115], v[114:115]
	v_mov_b64_e32 v[198:199], s[56:57]
	v_rcp_f32_e32 v244, v122
	v_add_u32_e32 v122, s42, v210
	v_rcp_f32_e32 v245, v123
	v_mad_i64_i32 v[122:123], s[26:27], v122, s61, v[198:199]
	v_lshl_add_u64 v[122:123], v[122:123], 0, s[40:41]
	v_lshl_add_u64 v[122:123], v[122:123], 0, s[6:7]
	v_rcp_f32_e32 v242, v124
	v_rcp_f32_e32 v243, v125
	v_rcp_f32_e32 v246, v126
	v_rcp_f32_e32 v247, v127
	v_rcp_f32_e32 v248, v128
	v_rcp_f32_e32 v249, v129
	v_lshl_add_u64 v[250:251], v[122:123], 0, v[186:187]
	v_or_b32_e32 v212, 16, v210
	v_ashrrev_i32_e32 v213, 31, v212
	v_add_u32_e32 v211, s42, v212
	s_waitcnt vmcnt(4)
	v_mov_b32_e32 v155, v154
	v_mov_b32_e32 v156, v154
	v_mov_b32_e32 v157, v154
	s_waitcnt vmcnt(3)
	s_nop 0
	v_mfma_f32_16x16x32_bf16 v[114:117], v[130:133], v[158:161], v[154:157]
	v_mfma_f32_16x16x32_bf16 v[118:121], v[134:137], v[158:161], v[154:157]
	s_waitcnt vmcnt(2)
	v_mfma_f32_16x16x32_bf16 v[114:117], v[142:145], v[170:173], v[114:117]
	v_mfma_f32_16x16x32_bf16 v[118:121], v[138:141], v[170:173], v[118:121]
	s_waitcnt vmcnt(1)
	v_mfma_f32_16x16x32_bf16 v[114:117], v[150:153], v[174:177], v[114:117]
	v_mfma_f32_16x16x32_bf16 v[226:229], v[146:149], v[174:177], v[118:121]
	global_load_dwordx4 v[174:177], v[216:217], off offset:256
	global_load_dwordx4 v[158:161], v[216:217], off offset:320
	global_load_dwordx4 v[170:173], v[220:221], off offset:256
	global_load_dwordx4 v[154:157], v[220:221], off offset:320
	s_waitcnt vmcnt(4)
; #define GAS __attribute__((address_space(1)))
; __device__ __forceinline__ v4u pack8(const float (&f)[8]) { v4u w; w.x = pk2(f[0], f[1]); w.y = pk2(f[2], f[3]); w.z = pk2(f[4], f[5]); w.w = pk2(f[6], f[7]); return w; }
; __device__ __forceinline__ float fexp2(float x) { return __builtin_amdgcn_exp2f(x); }
; __device__ __forceinline__ float frcp(float x) { return __builtin_amdgcn_rcpf(x); }
;     __device__ __forceinline__ void operator()(const af4 (&acc)[2][2][4][2], const pg8::Unit& u, int wr_, int wc_, int fr_, int fq_) const {
;     ...
;             for (int m = 0; m < 4; ++m) {
;                 if (ai == 0 && m == 0) load_raw(1);
;                 const int it = wr * 64 + m * 16 + fr;
;                 bf16x8 wf[4];
; #pragma unroll
;                 for (int ks = 0; ks < 4; ++ks) wf[ks] = *(const GAS bf16x8*)(wsg + (size_t)it * 128 + 32 * ks + 8 * fq);
;                 const float bsi = bs[grp * 128 + it];
;                 af4 vm[2] = {(af4){bsi, bsi, bsi, bsi}, (af4){bsi, bsi, bsi, bsi}};
; #pragma unroll
;                 for (int ks = 0; ks < 4; ++ks) {
; #pragma unroll
;                     for (int n = 0; n < 2; ++n) vm[n] = __builtin_amdgcn_mfma_f32_16x16x32_bf16(av[n][ks], wf[ks], vm[n], 0, 0, 0);
;                 }
;                 float o[8];
; #pragma unroll
;                 for (int n = 0; n < 2; ++n)
; #pragma unroll
;                     for (int e = 0; e < 4; e += 2) {
;                         const f32x2 uu = {acc[ai][0][m][n][e], acc[ai][0][m][n][e + 1]}, gg = {acc[ai][1][m][n][e], acc[ai][1][m][n][e + 1]}, vv = {vm[n][e], vm[n][e + 1]};
;                         const f32x2 ar = uu * (uu * uu * (-2.302208198f * 0.044715f) + (-2.302208198f));
;                         const f32x2 gs = gg * (-1.4426950408889634f);
;                         const f32x2 ea = {fexp2(ar.x), fexp2(ar.y)}, eb = {fexp2(gs.x), fexp2(gs.y)};
;                         const f32x2 q = eb + 1.0f, den = ea * q + q;
;                         const f32x2 r = {frcp(den.x), frcp(den.y)};
;                         const f32x2 w = (uu * gg) * vv * r;
;                         o[4 * n + e] = w.x; o[4 * n + e + 1] = w.y; }
;                 *(GAS v4u*)(Y + (size_t)(tok0 + it) * CW + chbase + 32 * wc + 8 * fq) = pack8(o);
	v_mfma_f32_16x16x32_bf16 v[230:233], v[166:169], v[222:225], v[114:117]
	global_load_dwordx4 v[126:129], v[216:217], off offset:384
	global_load_dwordx4 v[118:121], v[216:217], off offset:448
	global_load_dwordx4 v[122:125], v[220:221], off offset:384
	global_load_dwordx4 v[114:117], v[220:221], off offset:448
	v_mfma_f32_16x16x32_bf16 v[220:223], v[162:165], v[222:225], v[226:229]
	s_nop 2
	v_mul_f32_e64 v216, v234, v230
	v_mul_f32_e64 v217, v235, v231
	v_pk_mul_f32 v[224:225], v[236:237], v[232:233]
	v_pk_mul_f32 v[216:217], v[242:243], v[216:217]
	v_pk_mul_f32 v[224:225], v[244:245], v[224:225]
	v_pk_mul_f32 v[242:243], v[110:111], s[20:21] op_sel_hi:[1,0]
	v_pk_mul_f32 v[220:221], v[238:239], v[220:221]
	v_pk_mul_f32 v[222:223], v[240:241], v[222:223]
	v_pk_mul_f32 v[226:227], v[246:247], v[220:221]
	v_pk_mul_f32 v[228:229], v[248:249], v[222:223]
	v_cvt_pk_bf16_f32 v220, v216, v217
	v_cvt_pk_bf16_f32 v221, v224, v225
	v_cvt_pk_bf16_f32 v222, v226, v227
	v_lshlrev_b64 v[216:217], 8, v[212:213]
	v_cvt_pk_bf16_f32 v223, v228, v229
	global_store_dwordx4 v[250:251], v[220:223], off
	global_load_dword v220, v[200:201], off offset:64
	v_lshl_add_u64 v[216:217], v[218:219], 0, v[216:217]
	global_load_dwordx4 v[224:227], v[216:217], off
	global_load_dwordx4 v[228:231], v[216:217], off offset:64
	global_load_dwordx4 v[232:235], v[216:217], off offset:128
	global_load_dwordx4 v[236:239], v[216:217], off offset:192
	v_pk_mul_f32 v[222:223], v[108:109], v[108:109]
	v_pk_mul_f32 v[240:241], v[106:107], v[106:107]
	v_pk_mul_f32 v[244:245], v[112:113], s[20:21] op_sel_hi:[1,0]
	v_pk_mul_f32 v[248:249], v[102:103], v[102:103]
	v_pk_mul_f32 v[250:251], v[98:99], s[20:21] op_sel_hi:[1,0]
	v_pk_mul_f32 v[98:99], v[100:101], s[20:21] op_sel_hi:[1,0]
	v_pk_fma_f32 v[100:101], v[240:241], s[16:17], v[196:197] op_sel_hi:[1,0,0] neg_lo:[1,0,0] neg_hi:[1,0,0]
	v_pk_fma_f32 v[222:223], v[222:223], s[16:17], v[196:197] op_sel_hi:[1,0,0] neg_lo:[1,0,0] neg_hi:[1,0,0]
	v_exp_f32_e32 v240, v242
	v_exp_f32_e32 v241, v243
	v_exp_f32_e32 v242, v244
	v_exp_f32_e32 v243, v245
	v_pk_fma_f32 v[244:245], v[248:249], s[16:17], v[196:197] op_sel_hi:[1,0,0] neg_lo:[1,0,0] neg_hi:[1,0,0]
	v_exp_f32_e32 v248, v250
	v_exp_f32_e32 v249, v251
	v_exp_f32_e32 v250, v98
	v_exp_f32_e32 v251, v99
	v_pk_mul_f32 v[98:99], v[106:107], v[100:101]
	v_pk_mul_f32 v[100:101], v[108:109], v[222:223]
	v_pk_mul_f32 v[110:111], v[106:107], v[110:111]
	v_pk_mul_f32 v[112:113], v[108:109], v[112:113]
	v_pk_mul_f32 v[246:247], v[104:105], v[104:105]
	v_exp_f32_e32 v106, v98
	v_exp_f32_e32 v107, v99
	v_exp_f32_e32 v108, v100
	v_exp_f32_e32 v109, v101
	v_pk_fma_f32 v[246:247], v[246:247], s[16:17], v[196:197] op_sel_hi:[1,0,0] neg_lo:[1,0,0] neg_hi:[1,0,0]
	v_pk_mul_f32 v[102:103], v[102:103], v[244:245]
	v_pk_mul_f32 v[104:105], v[104:105], v[246:247]
	v_exp_f32_e32 v244, v102
	v_exp_f32_e32 v245, v103
	v_exp_f32_e32 v246, v104
	v_exp_f32_e32 v247, v105
	v_pk_add_f32 v[102:103], v[240:241], 1.0 op_sel_hi:[1,0]
	v_pk_add_f32 v[104:105], v[242:243], 1.0 op_sel_hi:[1,0]
	v_pk_fma_f32 v[106:107], v[106:107], v[102:103], v[102:103]
	v_pk_fma_f32 v[108:109], v[108:109], v[104:105], v[104:105]
	v_pk_add_f32 v[240:241], v[248:249], 1.0 op_sel_hi:[1,0]
	v_pk_add_f32 v[242:243], v[250:251], 1.0 op_sel_hi:[1,0]
	s_waitcnt vmcnt(4)
	v_mov_b32_e32 v221, v220
	v_mov_b32_e32 v222, v220
	v_mov_b32_e32 v223, v220
	s_waitcnt vmcnt(3)
	s_nop 0
	v_mfma_f32_16x16x32_bf16 v[98:101], v[130:133], v[224:227], v[220:223]
	v_mfma_f32_16x16x32_bf16 v[102:105], v[134:137], v[224:227], v[220:223]
	v_rcp_f32_e32 v224, v106
	v_rcp_f32_e32 v225, v107
	v_rcp_f32_e32 v226, v108
	s_waitcnt vmcnt(2)
	v_mfma_f32_16x16x32_bf16 v[98:101], v[142:145], v[228:231], v[98:101]
	v_rcp_f32_e32 v227, v109
	v_pk_fma_f32 v[220:221], v[244:245], v[240:241], v[240:241]
	v_pk_fma_f32 v[222:223], v[246:247], v[242:243], v[242:243]
	v_mfma_f32_16x16x32_bf16 v[102:105], v[138:141], v[228:231], v[102:105]
	v_rcp_f32_e32 v220, v220
	v_rcp_f32_e32 v221, v221
	v_rcp_f32_e32 v222, v222
	s_waitcnt vmcnt(1)
	v_mfma_f32_16x16x32_bf16 v[106:109], v[150:153], v[232:235], v[98:101]
	v_rcp_f32_e32 v223, v223
	v_mad_i64_i32 v[228:229], s[26:27], v211, s61, v[198:199]
	v_mfma_f32_16x16x32_bf16 v[100:103], v[146:149], v[232:235], v[102:105]
	v_or_b32_e32 v98, 32, v210
	v_ashrrev_i32_e32 v99, 31, v98
	v_pk_mul_f32 v[234:235], v[86:87], v[86:87]
	s_waitcnt vmcnt(0)
; #define GAS __attribute__((address_space(1)))
; __device__ __forceinline__ v4u pack8(const float (&f)[8]) { v4u w; w.x = pk2(f[0], f[1]); w.y = pk2(f[2], f[3]); w.z = pk2(f[4], f[5]); w.w = pk2(f[6], f[7]); return w; }
; __device__ __forceinline__ float fexp2(float x) { return __builtin_amdgcn_exp2f(x); }
; __device__ __forceinline__ float frcp(float x) { return __builtin_amdgcn_rcpf(x); }
;     __device__ __forceinline__ void operator()(const af4 (&acc)[2][2][4][2], const pg8::Unit& u, int wr_, int wc_, int fr_, int fq_) const {
;     ...
;             for (int m = 0; m < 4; ++m) {
;                 if (ai == 0 && m == 0) load_raw(1);
;                 const int it = wr * 64 + m * 16 + fr;
;                 bf16x8 wf[4];
; #pragma unroll
;                 for (int ks = 0; ks < 4; ++ks) wf[ks] = *(const GAS bf16x8*)(wsg + (size_t)it * 128 + 32 * ks + 8 * fq);
;                 const float bsi = bs[grp * 128 + it];
;                 af4 vm[2] = {(af4){bsi, bsi, bsi, bsi}, (af4){bsi, bsi, bsi, bsi}};
; #pragma unroll
;                 for (int ks = 0; ks < 4; ++ks) {
; #pragma unroll
;                     for (int n = 0; n < 2; ++n) vm[n] = __builtin_amdgcn_mfma_f32_16x16x32_bf16(av[n][ks], wf[ks], vm[n], 0, 0, 0);
;                 }
;                 float o[8];
; #pragma unroll
;                 for (int n = 0; n < 2; ++n)
; #pragma unroll
;                     for (int e = 0; e < 4; e += 2) {
;                         const f32x2 uu = {acc[ai][0][m][n][e], acc[ai][0][m][n][e + 1]}, gg = {acc[ai][1][m][n][e], acc[ai][1][m][n][e + 1]}, vv = {vm[n][e], vm[n][e + 1]};
;                         const f32x2 ar = uu * (uu * uu * (-2.302208198f * 0.044715f) + (-2.302208198f));
;                         const f32x2 gs = gg * (-1.4426950408889634f);
;                         const f32x2 ea = {fexp2(ar.x), fexp2(ar.y)}, eb = {fexp2(gs.x), fexp2(gs.y)};
;                         const f32x2 q = eb + 1.0f, den = ea * q + q;
;                         const f32x2 r = {frcp(den.x), frcp(den.y)};
;                         const f32x2 w = (uu * gg) * vv * r;
;                         o[4 * n + e] = w.x; o[4 * n + e + 1] = w.y; }
;                 *(GAS v4u*)(Y + (size_t)(tok0 + it) * CW + chbase + 32 * wc + 8 * fq) = pack8(o);
	v_mfma_f32_16x16x32_bf16 v[104:107], v[166:169], v[236:239], v[106:109]
	v_mul_f32_e64 v240, v88, v84
	v_mul_f32_e64 v241, v89, v85
	v_pk_mul_f32 v[232:233], v[88:89], v[88:89]
	v_mfma_f32_16x16x32_bf16 v[100:103], v[162:165], v[236:239], v[100:103]
	v_lshl_add_u64 v[108:109], v[228:229], 0, s[40:41]
	v_lshl_add_u64 v[108:109], v[108:109], 0, s[6:7]
	v_lshl_add_u64 v[108:109], v[108:109], 0, v[186:187]
	s_nop 0
	v_pk_mul_f32 v[104:105], v[110:111], v[104:105]
	v_pk_mul_f32 v[106:107], v[112:113], v[106:107]
	s_nop 1
	v_pk_mul_f32 v[100:101], v[252:253], v[100:101]
	v_pk_mul_f32 v[102:103], v[192:193], v[102:103]
	v_pk_mul_f32 v[104:105], v[224:225], v[104:105]
	v_pk_mul_f32 v[106:107], v[226:227], v[106:107]
	v_pk_mul_f32 v[110:111], v[220:221], v[100:101]
	v_pk_mul_f32 v[112:113], v[222:223], v[102:103]
	v_cvt_pk_bf16_f32 v100, v104, v105
	v_cvt_pk_bf16_f32 v101, v106, v107
	v_cvt_pk_bf16_f32 v102, v110, v111
	v_pk_mul_f32 v[106:107], v[90:91], v[90:91]
	v_cvt_pk_bf16_f32 v103, v112, v113
	global_store_dwordx4 v[108:109], v[100:103], off
	global_load_dword v104, v[200:201], off offset:128
	v_pk_mul_f32 v[112:113], v[94:95], s[20:21] op_sel_hi:[1,0]
	v_lshlrev_b64 v[100:101], 8, v[98:99]
	v_lshl_add_u64 v[102:103], v[218:219], 0, v[100:101]
	global_load_dwordx4 v[108:111], v[102:103], off
	global_load_dwordx4 v[220:223], v[102:103], off offset:64
	global_load_dwordx4 v[224:227], v[102:103], off offset:128
	global_load_dwordx4 v[228:231], v[102:103], off offset:192
	v_pk_mul_f32 v[100:101], v[92:93], v[92:93]
	v_pk_mul_f32 v[192:193], v[96:97], s[20:21] op_sel_hi:[1,0]
	v_pk_mul_f32 v[236:237], v[82:83], s[20:21] op_sel_hi:[1,0]
	v_pk_mul_f32 v[238:239], v[86:87], v[82:83]
	v_pk_mul_f32 v[82:83], v[84:85], s[20:21] op_sel_hi:[1,0]
	v_pk_fma_f32 v[84:85], v[106:107], s[16:17], v[196:197] op_sel_hi:[1,0,0] neg_lo:[1,0,0] neg_hi:[1,0,0]
	v_exp_f32_e32 v106, v112
	v_exp_f32_e32 v107, v113
	v_pk_fma_f32 v[100:101], v[100:101], s[16:17], v[196:197] op_sel_hi:[1,0,0] neg_lo:[1,0,0] neg_hi:[1,0,0]
	v_exp_f32_e32 v112, v192
	v_exp_f32_e32 v113, v193
	v_pk_fma_f32 v[192:193], v[234:235], s[16:17], v[196:197] op_sel_hi:[1,0,0] neg_lo:[1,0,0] neg_hi:[1,0,0]
	v_exp_f32_e32 v234, v236
	v_exp_f32_e32 v235, v237
	v_exp_f32_e32 v236, v82
	v_exp_f32_e32 v237, v83
	v_pk_mul_f32 v[82:83], v[90:91], v[84:85]
	v_pk_mul_f32 v[84:85], v[92:93], v[100:101]
	v_pk_mul_f32 v[94:95], v[90:91], v[94:95]
	v_pk_mul_f32 v[96:97], v[92:93], v[96:97]
	v_exp_f32_e32 v90, v82
	v_exp_f32_e32 v91, v83
	v_exp_f32_e32 v92, v84
	v_exp_f32_e32 v93, v85
	v_pk_fma_f32 v[232:233], v[232:233], s[16:17], v[196:197] op_sel_hi:[1,0,0] neg_lo:[1,0,0] neg_hi:[1,0,0]
	v_pk_mul_f32 v[86:87], v[86:87], v[192:193]
	v_pk_mul_f32 v[88:89], v[88:89], v[232:233]
	v_exp_f32_e32 v100, v86
	v_exp_f32_e32 v101, v87
	v_pk_add_f32 v[86:87], v[106:107], 1.0 op_sel_hi:[1,0]
	v_exp_f32_e32 v192, v88
	v_exp_f32_e32 v193, v89
	v_pk_add_f32 v[88:89], v[112:113], 1.0 op_sel_hi:[1,0]
	v_pk_fma_f32 v[90:91], v[90:91], v[86:87], v[86:87]
	v_pk_fma_f32 v[92:93], v[92:93], v[88:89], v[88:89]
	v_pk_add_f32 v[112:113], v[234:235], 1.0 op_sel_hi:[1,0]
	v_pk_add_f32 v[232:233], v[236:237], 1.0 op_sel_hi:[1,0]
	v_pk_fma_f32 v[100:101], v[100:101], v[112:113], v[112:113]
	v_rcp_f32_e32 v90, v90
	v_rcp_f32_e32 v91, v91
	v_rcp_f32_e32 v92, v92
	v_rcp_f32_e32 v93, v93
	v_add_u32_e32 v99, s42, v98
	v_pk_mul_f32 v[112:113], v[78:79], s[20:21] op_sel_hi:[1,0]
	v_pk_mul_f32 v[78:79], v[74:75], v[78:79]
	s_waitcnt vmcnt(4)
	v_mov_b32_e32 v105, v104
	v_mov_b32_e32 v106, v104
	v_mov_b32_e32 v107, v104
	s_waitcnt vmcnt(3)
	s_nop 0
	v_mfma_f32_16x16x32_bf16 v[82:85], v[130:133], v[108:111], v[104:107]
	v_mfma_f32_16x16x32_bf16 v[86:89], v[134:137], v[108:111], v[104:107]
	v_mad_i64_i32 v[108:109], s[26:27], v99, s61, v[198:199]
	v_lshl_add_u64 v[108:109], v[108:109], 0, s[40:41]
	s_waitcnt vmcnt(2)
	v_mfma_f32_16x16x32_bf16 v[82:85], v[142:145], v[220:223], v[82:85]
	v_fma_f32 v104, v192, v232, v232
	v_fma_f32 v105, v193, v233, v233
	v_rcp_f32_e32 v106, v100
	v_rcp_f32_e32 v107, v101
	v_mfma_f32_16x16x32_bf16 v[86:89], v[138:141], v[220:223], v[86:89]
	v_rcp_f32_e32 v104, v104
	v_rcp_f32_e32 v105, v105
	v_lshl_add_u64 v[108:109], v[108:109], 0, s[6:7]
	s_waitcnt vmcnt(1)
	v_mfma_f32_16x16x32_bf16 v[82:85], v[150:153], v[224:227], v[82:85]
	v_lshl_add_u64 v[108:109], v[108:109], 0, v[186:187]
	v_or_b32_e32 v100, 48, v210
	v_ashrrev_i32_e32 v101, 31, v100
	v_mfma_f32_16x16x32_bf16 v[86:89], v[146:149], v[224:227], v[86:89]
	v_mul_f32_e64 v110, v74, v74
	v_mul_f32_e64 v111, v75, v75
	v_pk_mul_f32 v[192:193], v[80:81], s[20:21] op_sel_hi:[1,0]
	v_pk_mul_f32 v[220:221], v[70:71], v[70:71]
	s_waitcnt vmcnt(0)
;     __device__ __forceinline__ void operator()(const af4 (&acc)[2][2][4][2], const pg8::Unit& u, int wr_, int wc_, int fr_, int fq_) const {
;     ...
;             const int tok0 = u.pm * 256 + ai * 128;
;             bf16x8 av[2][4];
; #pragma unroll
;             for (int ks = 0; ks < 4; ++ks) {
;                 const int j0 = tok0 + 32 * ks + 8 * fq;
;                 f32x4 st[4];
; #pragma unroll
;                 for (int q = 0; q < 4; ++q) st[q] = *(const GAS f32x4*)(stats + (size_t)(j0 + 2 * q) * 2);
; #pragma unroll
;                 for (int n = 0; n < 2; ++n) {
;                     float vf[8];
;                     unpack8(raw[n][ks], vf);
; #pragma unroll
;     ...
;             for (int m = 0; m < 4; ++m) {
;                 if (ai == 0 && m == 0) load_raw(1);
;                 const int it = wr * 64 + m * 16 + fr;
;                 bf16x8 wf[4];
; #pragma unroll
;                 for (int ks = 0; ks < 4; ++ks) wf[ks] = *(const GAS bf16x8*)(wsg + (size_t)it * 128 + 32 * ks + 8 * fq);
;                 const float bsi = bs[grp * 128 + it];
;                 af4 vm[2] = {(af4){bsi, bsi, bsi, bsi}, (af4){bsi, bsi, bsi, bsi}};
; #pragma unroll
;                 for (int ks = 0; ks < 4; ++ks) {
; #pragma unroll
;                     for (int n = 0; n < 2; ++n) vm[n] = __builtin_amdgcn_mfma_f32_16x16x32_bf16(av[n][ks], wf[ks], vm[n], 0, 0, 0);
;                 }
;                 float o[8];
; #pragma unroll
;                 for (int n = 0; n < 2; ++n)
; #pragma unroll
;                     for (int e = 0; e < 4; e += 2) {
;                         const f32x2 uu = {acc[ai][0][m][n][e], acc[ai][0][m][n][e + 1]}, gg = {acc[ai][1][m][n][e], acc[ai][1][m][n][e + 1]}, vv = {vm[n][e], vm[n][e + 1]};
;                         const f32x2 ar = uu * (uu * uu * (-2.302208198f * 0.044715f) + (-2.302208198f));
;                         const f32x2 gs = gg * (-1.4426950408889634f);
;                         const f32x2 ea = {fexp2(ar.x), fexp2(ar.y)}, eb = {fexp2(gs.x), fexp2(gs.y)};
;                         const f32x2 q = eb + 1.0f, den = ea * q + q;
;                         const f32x2 r = {frcp(den.x), frcp(den.y)};
;                         const f32x2 w = (uu * gg) * vv * r;
;                         o[4 * n + e] = w.x; o[4 * n + e + 1] = w.y; }
;                 *(GAS v4u*)(Y + (size_t)(tok0 + it) * CW + chbase + 32 * wc + 8 * fq) = pack8(o);
	v_mfma_f32_16x16x32_bf16 v[82:85], v[166:169], v[228:231], v[82:85]
	v_mul_f32_e64 v222, v66, s20
	v_mul_f32_e64 v223, v67, s20
	v_pk_mul_f32 v[224:225], v[70:71], v[66:67]
	v_pk_mul_f32 v[66:67], v[68:69], s[20:21] op_sel_hi:[1,0]
	v_mfma_f32_16x16x32_bf16 v[86:89], v[162:165], v[228:231], v[86:89]
	v_mul_f32_e64 v226, v72, v68
	v_mul_f32_e64 v227, v73, v69
	s_nop 0
	v_pk_mul_f32 v[82:83], v[94:95], v[82:83]
	v_pk_mul_f32 v[84:85], v[96:97], v[84:85]
	v_pk_mul_f32 v[82:83], v[90:91], v[82:83]
	v_pk_mul_f32 v[84:85], v[92:93], v[84:85]
	s_nop 0
	v_pk_mul_f32 v[86:87], v[238:239], v[86:87]
	v_pk_mul_f32 v[88:89], v[240:241], v[88:89]
	v_pk_mul_f32 v[86:87], v[106:107], v[86:87]
	v_pk_mul_f32 v[88:89], v[104:105], v[88:89]
	v_cvt_pk_bf16_f32 v82, v82, v83
	v_cvt_pk_bf16_f32 v83, v84, v85
	v_cvt_pk_bf16_f32 v84, v86, v87
	v_pk_fma_f32 v[68:69], v[110:111], s[16:17], v[196:197] op_sel_hi:[1,0,0] neg_lo:[1,0,0] neg_hi:[1,0,0]
	v_cvt_pk_bf16_f32 v85, v88, v89
	global_store_dwordx4 v[108:109], v[82:85], off
	global_load_dword v82, v[200:201], off offset:192
	v_exp_f32_e32 v110, v112
	v_lshlrev_b64 v[84:85], 8, v[100:101]
	v_lshl_add_u64 v[104:105], v[218:219], 0, v[84:85]
	global_load_dwordx4 v[86:89], v[104:105], off
	global_load_dwordx4 v[90:93], v[104:105], off offset:64
	global_load_dwordx4 v[94:97], v[104:105], off offset:128
	global_load_dwordx4 v[106:109], v[104:105], off offset:192
	v_pk_mul_f32 v[84:85], v[76:77], v[76:77]
	v_pk_mul_f32 v[218:219], v[72:73], v[72:73]
	v_exp_f32_e32 v111, v113
	v_pk_fma_f32 v[84:85], v[84:85], s[16:17], v[196:197] op_sel_hi:[1,0,0] neg_lo:[1,0,0] neg_hi:[1,0,0]
	v_exp_f32_e32 v112, v192
	v_exp_f32_e32 v113, v193
	v_pk_fma_f32 v[192:193], v[220:221], s[16:17], v[196:197] op_sel_hi:[1,0,0] neg_lo:[1,0,0] neg_hi:[1,0,0]
	v_pk_fma_f32 v[218:219], v[218:219], s[16:17], v[196:197] op_sel_hi:[1,0,0] neg_lo:[1,0,0] neg_hi:[1,0,0]
	v_pk_mul_f32 v[68:69], v[74:75], v[68:69]
	v_exp_f32_e32 v220, v222
	v_exp_f32_e32 v221, v223
	v_exp_f32_e32 v66, v66
	v_exp_f32_e32 v67, v67
	v_pk_mul_f32 v[74:75], v[76:77], v[84:85]
	v_pk_mul_f32 v[70:71], v[70:71], v[192:193]
	v_pk_mul_f32 v[72:73], v[72:73], v[218:219]
	v_exp_f32_e32 v68, v68
	v_exp_f32_e32 v69, v69
	v_exp_f32_e32 v74, v74
	v_exp_f32_e32 v75, v75
	v_exp_f32_e32 v70, v70
	v_exp_f32_e32 v71, v71
	v_exp_f32_e32 v72, v72
	v_exp_f32_e32 v73, v73
	v_pk_mul_f32 v[80:81], v[76:77], v[80:81]
	v_pk_add_f32 v[76:77], v[110:111], 1.0 op_sel_hi:[1,0]
	v_pk_add_f32 v[110:111], v[112:113], 1.0 op_sel_hi:[1,0]
	v_pk_add_f32 v[112:113], v[220:221], 1.0 op_sel_hi:[1,0]
	v_pk_add_f32 v[192:193], v[66:67], 1.0 op_sel_hi:[1,0]
	v_pk_fma_f32 v[76:77], v[68:69], v[76:77], v[76:77]
	v_pk_fma_f32 v[74:75], v[74:75], v[110:111], v[110:111]
	v_pk_fma_f32 v[110:111], v[70:71], v[112:113], v[112:113]
	v_pk_fma_f32 v[112:113], v[72:73], v[192:193], v[192:193]
	v_rcp_f32_e32 v76, v76
	v_rcp_f32_e32 v77, v77
	v_rcp_f32_e32 v74, v74
	v_rcp_f32_e32 v75, v75
	v_add_u32_e32 v99, s23, v210
	s_waitcnt vmcnt(4)
	v_mov_b32_e32 v83, v82
	v_mov_b32_e32 v84, v82
	v_mov_b32_e32 v85, v82
	s_waitcnt vmcnt(3)
	s_nop 0
	v_mfma_f32_16x16x32_bf16 v[66:69], v[130:133], v[86:89], v[82:85]
	v_lshlrev_b32_e32 v130, 16, v156
	v_and_b32_e32 v131, 0xffff0000, v156
	v_lshlrev_b32_e32 v132, 16, v157
	v_mfma_f32_16x16x32_bf16 v[70:73], v[134:137], v[86:89], v[82:85]
	v_rcp_f32_e32 v86, v112
	v_rcp_f32_e32 v87, v113
	v_lshlrev_b32_e32 v112, 16, v155
	s_waitcnt vmcnt(2)
	v_mfma_f32_16x16x32_bf16 v[66:69], v[142:145], v[90:93], v[66:69]
	v_rcp_f32_e32 v84, v110
	v_rcp_f32_e32 v85, v111
	v_or_b32_e32 v82, s23, v209
	v_mfma_f32_16x16x32_bf16 v[70:73], v[138:141], v[90:93], v[70:73]
	v_add_u32_e32 v90, s42, v100
	v_mad_i64_i32 v[90:91], s[26:27], v90, s61, v[198:199]
	s_waitcnt vmcnt(1)
	v_mfma_f32_16x16x32_bf16 v[66:69], v[150:153], v[94:97], v[66:69]
	v_lshl_add_u64 v[90:91], v[90:91], 0, s[40:41]
	v_lshl_add_u64 v[90:91], v[90:91], 0, s[6:7]
	v_ashrrev_i32_e32 v83, 31, v82
	v_mfma_f32_16x16x32_bf16 v[70:73], v[146:149], v[94:97], v[70:73]
	v_lshl_add_u64 v[90:91], v[90:91], 0, v[186:187]
	v_lshl_add_u32 v88, v82, 3, s98
	v_lshlrev_b32_e32 v92, 16, v177
	s_waitcnt vmcnt(0)
	v_mfma_f32_16x16x32_bf16 v[66:69], v[166:169], v[106:109], v[66:69]
	v_and_b32_e32 v93, 0xffff0000, v177
	v_lshlrev_b32_e32 v94, 16, v170
	v_and_b32_e32 v95, 0xffff0000, v170
	v_mfma_f32_16x16x32_bf16 v[70:73], v[162:165], v[106:109], v[70:73]
	v_lshlrev_b32_e32 v96, 16, v171
	s_nop 2
	v_pk_mul_f32 v[66:67], v[78:79], v[66:67]
	v_pk_mul_f32 v[68:69], v[80:81], v[68:69]
	v_pk_mul_f32 v[66:67], v[76:77], v[66:67]
	v_pk_mul_f32 v[68:69], v[74:75], v[68:69]
	v_pk_mul_f32 v[70:71], v[224:225], v[70:71]
	v_pk_mul_f32 v[72:73], v[226:227], v[72:73]
	v_pk_mul_f32 v[70:71], v[84:85], v[70:71]
	v_pk_mul_f32 v[72:73], v[86:87], v[72:73]
	v_cvt_pk_bf16_f32 v66, v66, v67
	v_cvt_pk_bf16_f32 v67, v68, v69
	v_cvt_pk_bf16_f32 v68, v70, v71
	v_or_b32_e32 v84, 32, v82
	v_cvt_pk_bf16_f32 v69, v72, v73
	global_store_dwordx4 v[90:91], v[66:69], off
	ds_read_b128 v[66:69], v88
	s_nop 0
	ds_read_b128 v[70:73], v88 offset:16
	ds_read_b128 v[74:77], v88 offset:32
	ds_read_b128 v[78:81], v88 offset:48
	v_ashrrev_i32_e32 v85, 31, v84
	v_lshl_add_u32 v88, v84, 3, s98
	v_lshlrev_b32_e32 v84, 16, v174
	v_and_b32_e32 v85, 0xffff0000, v174
	v_lshlrev_b32_e32 v86, 16, v175
	v_and_b32_e32 v87, 0xffff0000, v175
	v_lshlrev_b32_e32 v90, 16, v176
	v_and_b32_e32 v91, 0xffff0000, v176
	v_and_b32_e32 v97, 0xffff0000, v171
	v_lshlrev_b32_e32 v106, 16, v172
	v_and_b32_e32 v107, 0xffff0000, v172
	v_lshlrev_b32_e32 v108, 16, v173
	v_and_b32_e32 v109, 0xffff0000, v173
	v_lshlrev_b32_e32 v110, 16, v154
	v_and_b32_e32 v111, 0xffff0000, v154
	v_and_b32_e32 v113, 0xffff0000, v155
	v_and_b32_e32 v133, 0xffff0000, v157
	v_pk_mul_f32 v[134:135], v[54:55], v[54:55]
	v_pk_mul_f32 v[136:137], v[50:51], s[20:21] op_sel_hi:[1,0]
	v_pk_mul_f32 v[138:139], v[54:55], v[50:51]
	v_pk_mul_f32 v[50:51], v[52:53], s[20:21] op_sel_hi:[1,0]
	v_pk_mul_f32 v[140:141], v[56:57], v[52:53]
	s_waitcnt lgkmcnt(3)
; #define GAS __attribute__((address_space(1)))
; __device__ __forceinline__ void unpack8(const v4u w, float (&f)[8]) { f[0] = bflo(w.x); f[1] = bfhi(w.x); f[2] = bflo(w.y); f[3] = bfhi(w.y); f[4] = bflo(w.z); f[5] = bfhi(w.z); f[6] = bflo(w.w); f[7] = bfhi(w.w); }
; __device__ __forceinline__ v4u pack8(const float (&f)[8]) { v4u w; w.x = pk2(f[0], f[1]); w.y = pk2(f[2], f[3]); w.z = pk2(f[4], f[5]); w.w = pk2(f[6], f[7]); return w; }
;     __device__ __forceinline__ void operator()(const af4 (&acc)[2][2][4][2], const pg8::Unit& u, int wr_, int wc_, int fr_, int fq_) const {
;     ...
;             for (int ks = 0; ks < 4; ++ks) {
;                 const int j0 = tok0 + 32 * ks + 8 * fq;
;                 f32x4 st[4];
; #pragma unroll
;                 for (int q = 0; q < 4; ++q) st[q] = *(const GAS f32x4*)(stats + (size_t)(j0 + 2 * q) * 2);
; #pragma unroll
;                 for (int n = 0; n < 2; ++n) {
;                     float vf[8];
;                     unpack8(raw[n][ks], vf);
; #pragma unroll
;                     for (int q = 0; q < 4; ++q) { f32x2 t = {vf[2 * q], vf[2 * q + 1]}; t = t * (f32x2){st[q].z, st[q].w} + (f32x2){st[q].x, st[q].y}; t = t * lg[n] + lb[n]; vf[2 * q] = t.x; vf[2 * q + 1] = t.y; }
;                     av[n][ks] = __builtin_bit_cast(bf16x8, pack8(vf));
	v_pk_fma_f32 v[84:85], v[68:69], v[84:85], v[66:67]
	s_waitcnt lgkmcnt(2)
	v_pk_fma_f32 v[86:87], v[72:73], v[86:87], v[70:71]
	s_waitcnt lgkmcnt(1)
	v_pk_fma_f32 v[90:91], v[76:77], v[90:91], v[74:75]
	s_waitcnt lgkmcnt(0)
	v_pk_fma_f32 v[92:93], v[80:81], v[92:93], v[78:79]
	v_pk_fma_f32 v[66:67], v[68:69], v[94:95], v[66:67]
	v_pk_fma_f32 v[68:69], v[72:73], v[96:97], v[70:71]
	v_pk_fma_f32 v[70:71], v[76:77], v[106:107], v[74:75]
	v_pk_fma_f32 v[72:73], v[80:81], v[108:109], v[78:79]
	v_pk_fma_f32 v[74:75], v[208:209], v[84:85], v[206:207] op_sel_hi:[0,1,0]
	v_pk_fma_f32 v[76:77], v[208:209], v[86:87], v[206:207] op_sel_hi:[0,1,0]
	v_pk_fma_f32 v[78:79], v[208:209], v[90:91], v[206:207] op_sel_hi:[0,1,0]
	v_pk_fma_f32 v[80:81], v[208:209], v[92:93], v[206:207] op_sel_hi:[0,1,0]
	v_pk_fma_f32 v[66:67], v[202:203], v[66:67], v[204:205] op_sel_hi:[0,1,0]
	v_pk_fma_f32 v[68:69], v[202:203], v[68:69], v[204:205] op_sel_hi:[0,1,0]
	v_pk_fma_f32 v[84:85], v[202:203], v[70:71], v[204:205] op_sel_hi:[0,1,0]
	v_pk_fma_f32 v[86:87], v[202:203], v[72:73], v[204:205] op_sel_hi:[0,1,0]
	v_cvt_pk_bf16_f32 v70, v74, v75
	v_cvt_pk_bf16_f32 v71, v76, v77
	v_cvt_pk_bf16_f32 v72, v78, v79
	v_cvt_pk_bf16_f32 v73, v80, v81
	v_cvt_pk_bf16_f32 v66, v66, v67
	v_cvt_pk_bf16_f32 v67, v68, v69
	v_cvt_pk_bf16_f32 v68, v84, v85
	v_cvt_pk_bf16_f32 v69, v86, v87
	ds_read_b128 v[74:77], v88
	ds_read_b128 v[78:81], v88 offset:16
	ds_read_b128 v[84:87], v88 offset:32
	s_nop 0
	ds_read_b128 v[88:91], v88 offset:48
	v_or_b32_e32 v92, 64, v82
	v_ashrrev_i32_e32 v93, 31, v92
	v_lshl_add_u32 v96, v92, 3, s98
	v_lshlrev_b32_e32 v92, 16, v158
	v_and_b32_e32 v93, 0xffff0000, v158
	v_lshlrev_b32_e32 v94, 16, v159
	v_and_b32_e32 v95, 0xffff0000, v159
	v_lshlrev_b32_e32 v106, 16, v160
	v_and_b32_e32 v107, 0xffff0000, v160
	v_lshlrev_b32_e32 v108, 16, v161
	v_and_b32_e32 v109, 0xffff0000, v161
	v_or_b32_e32 v82, 0x60, v82
	v_ashrrev_i32_e32 v83, 31, v82
	s_waitcnt lgkmcnt(3)
	v_pk_fma_f32 v[92:93], v[76:77], v[92:93], v[74:75]
	s_waitcnt lgkmcnt(2)
	v_pk_fma_f32 v[94:95], v[80:81], v[94:95], v[78:79]
	s_waitcnt lgkmcnt(1)
	v_pk_fma_f32 v[106:107], v[86:87], v[106:107], v[84:85]
	s_waitcnt lgkmcnt(0)
	v_pk_fma_f32 v[108:109], v[90:91], v[108:109], v[88:89]
	v_pk_fma_f32 v[74:75], v[76:77], v[110:111], v[74:75]
	v_pk_fma_f32 v[76:77], v[80:81], v[112:113], v[78:79]
	v_pk_fma_f32 v[78:79], v[86:87], v[130:131], v[84:85]
	v_pk_fma_f32 v[80:81], v[90:91], v[132:133], v[88:89]
	v_pk_fma_f32 v[84:85], v[208:209], v[92:93], v[206:207] op_sel_hi:[0,1,0]
	v_pk_fma_f32 v[86:87], v[208:209], v[94:95], v[206:207] op_sel_hi:[0,1,0]
	v_pk_fma_f32 v[88:89], v[208:209], v[106:107], v[206:207] op_sel_hi:[0,1,0]
	v_pk_fma_f32 v[90:91], v[208:209], v[108:109], v[206:207] op_sel_hi:[0,1,0]
	v_pk_fma_f32 v[74:75], v[202:203], v[74:75], v[204:205] op_sel_hi:[0,1,0]
	v_pk_fma_f32 v[76:77], v[202:203], v[76:77], v[204:205] op_sel_hi:[0,1,0]
	v_pk_fma_f32 v[92:93], v[202:203], v[78:79], v[204:205] op_sel_hi:[0,1,0]
	v_pk_fma_f32 v[94:95], v[202:203], v[80:81], v[204:205] op_sel_hi:[0,1,0]
	v_cvt_pk_bf16_f32 v78, v84, v85
	v_cvt_pk_bf16_f32 v79, v86, v87
	v_cvt_pk_bf16_f32 v80, v88, v89
	v_cvt_pk_bf16_f32 v81, v90, v91
	v_cvt_pk_bf16_f32 v74, v74, v75
	v_cvt_pk_bf16_f32 v75, v76, v77
	v_cvt_pk_bf16_f32 v76, v92, v93
	v_cvt_pk_bf16_f32 v77, v94, v95
	ds_read_b128 v[84:87], v96
	ds_read_b128 v[88:91], v96 offset:16
	ds_read_b128 v[92:95], v96 offset:32
	ds_read_b128 v[106:109], v96 offset:48
	v_lshl_add_u32 v110, v82, 3, s98
	v_lshlrev_b32_e32 v82, 16, v126
	v_and_b32_e32 v83, 0xffff0000, v126
	v_lshlrev_b32_e32 v96, 16, v127
	v_and_b32_e32 v97, 0xffff0000, v127
	v_lshlrev_b32_e32 v112, 16, v128
	v_and_b32_e32 v113, 0xffff0000, v128
	v_lshlrev_b32_e32 v126, 16, v129
	v_and_b32_e32 v127, 0xffff0000, v129
	v_lshlrev_b32_e32 v128, 16, v122
	v_and_b32_e32 v129, 0xffff0000, v122
	v_lshlrev_b32_e32 v122, 16, v123
	v_and_b32_e32 v123, 0xffff0000, v123
	v_lshlrev_b32_e32 v130, 16, v124
	v_and_b32_e32 v131, 0xffff0000, v124
	v_lshlrev_b32_e32 v124, 16, v125
	v_and_b32_e32 v125, 0xffff0000, v125
	v_pk_mul_f32 v[132:133], v[56:57], v[56:57]
	s_waitcnt lgkmcnt(3)
	v_pk_fma_f32 v[82:83], v[86:87], v[82:83], v[84:85]
	s_waitcnt lgkmcnt(2)
	v_pk_fma_f32 v[96:97], v[90:91], v[96:97], v[88:89]
	s_waitcnt lgkmcnt(1)
	v_pk_fma_f32 v[112:113], v[94:95], v[112:113], v[92:93]
	s_waitcnt lgkmcnt(0)
	v_pk_fma_f32 v[126:127], v[108:109], v[126:127], v[106:107]
	v_pk_fma_f32 v[84:85], v[86:87], v[128:129], v[84:85]
	v_pk_fma_f32 v[86:87], v[90:91], v[122:123], v[88:89]
	v_pk_fma_f32 v[88:89], v[94:95], v[130:131], v[92:93]
	v_pk_fma_f32 v[90:91], v[108:109], v[124:125], v[106:107]
	v_pk_fma_f32 v[82:83], v[208:209], v[82:83], v[206:207] op_sel_hi:[0,1,0]
	v_pk_fma_f32 v[92:93], v[208:209], v[96:97], v[206:207] op_sel_hi:[0,1,0]
	v_pk_fma_f32 v[94:95], v[208:209], v[112:113], v[206:207] op_sel_hi:[0,1,0]
	v_pk_fma_f32 v[96:97], v[208:209], v[126:127], v[206:207] op_sel_hi:[0,1,0]
	v_pk_fma_f32 v[84:85], v[202:203], v[84:85], v[204:205] op_sel_hi:[0,1,0]
	v_pk_fma_f32 v[106:107], v[202:203], v[86:87], v[204:205] op_sel_hi:[0,1,0]
	v_pk_fma_f32 v[108:109], v[202:203], v[88:89], v[204:205] op_sel_hi:[0,1,0]
	v_pk_fma_f32 v[90:91], v[202:203], v[90:91], v[204:205] op_sel_hi:[0,1,0]
	v_cvt_pk_bf16_f32 v86, v82, v83
	v_cvt_pk_bf16_f32 v87, v92, v93
	v_cvt_pk_bf16_f32 v88, v94, v95
	v_cvt_pk_bf16_f32 v89, v96, v97
	v_cvt_pk_bf16_f32 v82, v84, v85
	v_cvt_pk_bf16_f32 v83, v106, v107
	v_cvt_pk_bf16_f32 v84, v108, v109
	v_cvt_pk_bf16_f32 v85, v90, v91
	ds_read_b128 v[90:93], v110
	ds_read_b128 v[94:97], v110 offset:16
	ds_read_b128 v[106:109], v110 offset:32
	s_nop 0
	ds_read_b128 v[110:113], v110 offset:48
	v_lshlrev_b32_e32 v122, 16, v118
	v_and_b32_e32 v123, 0xffff0000, v118
	v_lshlrev_b32_e32 v118, 16, v119
	v_and_b32_e32 v119, 0xffff0000, v119
	v_lshlrev_b32_e32 v124, 16, v120
	v_and_b32_e32 v125, 0xffff0000, v120
	v_lshlrev_b32_e32 v120, 16, v121
	v_and_b32_e32 v121, 0xffff0000, v121
	v_lshlrev_b32_e32 v126, 16, v114
	v_and_b32_e32 v127, 0xffff0000, v114
	v_lshlrev_b32_e32 v114, 16, v115
	v_and_b32_e32 v115, 0xffff0000, v115
	v_lshlrev_b32_e32 v128, 16, v116
	v_and_b32_e32 v129, 0xffff0000, v116
	v_lshlrev_b32_e32 v116, 16, v117
	v_and_b32_e32 v117, 0xffff0000, v117
	v_pk_mul_f32 v[130:131], v[64:65], s[20:21] op_sel_hi:[1,0]
	v_pk_fma_f32 v[132:133], v[132:133], s[16:17], v[196:197] op_sel_hi:[1,0,0] neg_lo:[1,0,0] neg_hi:[1,0,0]
	v_pk_mul_f32 v[64:65], v[60:61], v[64:65]
	v_pk_mul_f32 v[56:57], v[56:57], v[132:133]
	s_waitcnt lgkmcnt(3)
; #define GAS __attribute__((address_space(1)))
; __device__ __forceinline__ v4u pack8(const float (&f)[8]) { v4u w; w.x = pk2(f[0], f[1]); w.y = pk2(f[2], f[3]); w.z = pk2(f[4], f[5]); w.w = pk2(f[6], f[7]); return w; }
; __device__ __forceinline__ float fexp2(float x) { return __builtin_amdgcn_exp2f(x); }
; __device__ __forceinline__ float frcp(float x) { return __builtin_amdgcn_rcpf(x); }
;     __device__ __forceinline__ void operator()(const af4 (&acc)[2][2][4][2], const pg8::Unit& u, int wr_, int wc_, int fr_, int fq_) const {
;     ...
;             for (int m = 0; m < 4; ++m) {
;                 if (ai == 0 && m == 0) load_raw(1);
;                 const int it = wr * 64 + m * 16 + fr;
;                 bf16x8 wf[4];
; #pragma unroll
;                 for (int ks = 0; ks < 4; ++ks) wf[ks] = *(const GAS bf16x8*)(wsg + (size_t)it * 128 + 32 * ks + 8 * fq);
;                 const float bsi = bs[grp * 128 + it];
;                 af4 vm[2] = {(af4){bsi, bsi, bsi, bsi}, (af4){bsi, bsi, bsi, bsi}};
; #pragma unroll
;                 for (int ks = 0; ks < 4; ++ks) {
; #pragma unroll
;                     for (int n = 0; n < 2; ++n) vm[n] = __builtin_amdgcn_mfma_f32_16x16x32_bf16(av[n][ks], wf[ks], vm[n], 0, 0, 0);
;                 }
;                 float o[8];
; #pragma unroll
;                 for (int n = 0; n < 2; ++n)
; #pragma unroll
;                     for (int e = 0; e < 4; e += 2) {
;                         const f32x2 uu = {acc[ai][0][m][n][e], acc[ai][0][m][n][e + 1]}, gg = {acc[ai][1][m][n][e], acc[ai][1][m][n][e + 1]}, vv = {vm[n][e], vm[n][e + 1]};
;                         const f32x2 ar = uu * (uu * uu * (-2.302208198f * 0.044715f) + (-2.302208198f));
;                         const f32x2 gs = gg * (-1.4426950408889634f);
;                         const f32x2 ea = {fexp2(ar.x), fexp2(ar.y)}, eb = {fexp2(gs.x), fexp2(gs.y)};
;                         const f32x2 q = eb + 1.0f, den = ea * q + q;
;                         const f32x2 r = {frcp(den.x), frcp(den.y)};
;                         const f32x2 w = (uu * gg) * vv * r;
;                         o[4 * n + e] = w.x; o[4 * n + e + 1] = w.y; }
;                 *(GAS v4u*)(Y + (size_t)(tok0 + it) * CW + chbase + 32 * wc + 8 * fq) = pack8(o);
	v_pk_fma_f32 v[122:123], v[92:93], v[122:123], v[90:91]
	s_waitcnt lgkmcnt(2)
	v_pk_fma_f32 v[118:119], v[96:97], v[118:119], v[94:95]
	s_waitcnt lgkmcnt(1)
	v_pk_fma_f32 v[124:125], v[108:109], v[124:125], v[106:107]
	s_waitcnt lgkmcnt(0)
	v_pk_fma_f32 v[120:121], v[112:113], v[120:121], v[110:111]
	v_pk_fma_f32 v[90:91], v[92:93], v[126:127], v[90:91]
	v_pk_fma_f32 v[92:93], v[96:97], v[114:115], v[94:95]
	v_pk_fma_f32 v[94:95], v[108:109], v[128:129], v[106:107]
	v_pk_fma_f32 v[96:97], v[112:113], v[116:117], v[110:111]
	v_pk_fma_f32 v[106:107], v[208:209], v[122:123], v[206:207] op_sel_hi:[0,1,0]
	v_pk_fma_f32 v[108:109], v[208:209], v[118:119], v[206:207] op_sel_hi:[0,1,0]
	v_pk_fma_f32 v[110:111], v[208:209], v[124:125], v[206:207] op_sel_hi:[0,1,0]
	v_pk_fma_f32 v[112:113], v[208:209], v[120:121], v[206:207] op_sel_hi:[0,1,0]
	v_pk_fma_f32 v[114:115], v[202:203], v[90:91], v[204:205] op_sel_hi:[0,1,0]
	v_pk_fma_f32 v[116:117], v[202:203], v[92:93], v[204:205] op_sel_hi:[0,1,0]
	v_pk_fma_f32 v[118:119], v[202:203], v[94:95], v[204:205] op_sel_hi:[0,1,0]
	v_pk_fma_f32 v[120:121], v[202:203], v[96:97], v[204:205] op_sel_hi:[0,1,0]
	v_cvt_pk_bf16_f32 v90, v106, v107
	v_cvt_pk_bf16_f32 v91, v108, v109
	v_cvt_pk_bf16_f32 v92, v110, v111
	v_cvt_pk_bf16_f32 v93, v112, v113
	v_cvt_pk_bf16_f32 v94, v114, v115
	v_cvt_pk_bf16_f32 v95, v116, v117
	v_cvt_pk_bf16_f32 v96, v118, v119
	v_cvt_pk_bf16_f32 v97, v120, v121
	global_load_dword v106, v[200:201], off
	global_load_dwordx4 v[110:113], v[214:215], off
	global_load_dwordx4 v[114:117], v[214:215], off offset:64
	global_load_dwordx4 v[118:121], v[214:215], off offset:128
	global_load_dwordx4 v[122:125], v[214:215], off offset:192
	v_pk_mul_f32 v[108:109], v[60:61], v[60:61]
	v_pk_mul_f32 v[126:127], v[58:59], v[58:59]
	v_pk_mul_f32 v[128:129], v[62:63], s[20:21] op_sel_hi:[1,0]
	v_pk_fma_f32 v[52:53], v[126:127], s[16:17], v[196:197] op_sel_hi:[1,0,0] neg_lo:[1,0,0] neg_hi:[1,0,0]
	v_pk_fma_f32 v[108:109], v[108:109], s[16:17], v[196:197] op_sel_hi:[1,0,0] neg_lo:[1,0,0] neg_hi:[1,0,0]
	v_exp_f32_e32 v126, v128
	v_exp_f32_e32 v127, v129
	v_exp_f32_e32 v128, v130
	v_exp_f32_e32 v129, v131
	v_pk_fma_f32 v[130:131], v[134:135], s[16:17], v[196:197] op_sel_hi:[1,0,0] neg_lo:[1,0,0] neg_hi:[1,0,0]
	v_exp_f32_e32 v134, v136
	v_exp_f32_e32 v135, v137
	v_exp_f32_e32 v136, v50
	v_exp_f32_e32 v137, v51
	v_pk_mul_f32 v[50:51], v[58:59], v[52:53]
	v_pk_mul_f32 v[52:53], v[60:61], v[108:109]
	v_pk_mul_f32 v[62:63], v[58:59], v[62:63]
	v_pk_mul_f32 v[54:55], v[54:55], v[130:131]
	v_exp_f32_e32 v58, v50
	v_exp_f32_e32 v59, v51
	v_exp_f32_e32 v60, v52
	v_exp_f32_e32 v61, v53
	v_exp_f32_e32 v130, v54
	v_exp_f32_e32 v131, v55
	v_exp_f32_e32 v132, v56
	v_exp_f32_e32 v133, v57
	v_pk_add_f32 v[126:127], v[126:127], 1.0 op_sel_hi:[1,0]
	v_pk_add_f32 v[128:129], v[128:129], 1.0 op_sel_hi:[1,0]
	v_pk_add_f32 v[134:135], v[134:135], 1.0 op_sel_hi:[1,0]
	v_pk_add_f32 v[136:137], v[136:137], 1.0 op_sel_hi:[1,0]
	v_pk_fma_f32 v[58:59], v[58:59], v[126:127], v[126:127]
	v_pk_fma_f32 v[60:61], v[60:61], v[128:129], v[128:129]
	v_rcp_f32_e32 v58, v58
	v_rcp_f32_e32 v59, v59
	v_rcp_f32_e32 v60, v60
	v_rcp_f32_e32 v61, v61
	s_waitcnt vmcnt(4)
	v_mov_b32_e32 v107, v106
	v_mov_b32_e32 v108, v106
	v_mov_b32_e32 v109, v106
	s_waitcnt vmcnt(3)
	s_nop 0
	v_mfma_f32_16x16x32_bf16 v[50:53], v[70:73], v[110:113], v[106:109]
	v_mfma_f32_16x16x32_bf16 v[54:57], v[66:69], v[110:113], v[106:109]
	v_mad_i64_i32 v[110:111], s[26:27], v99, s61, v[198:199]
	v_lshl_add_u64 v[110:111], v[110:111], 0, s[40:41]
	s_waitcnt vmcnt(2)
	v_mfma_f32_16x16x32_bf16 v[50:53], v[78:81], v[114:117], v[50:53]
	v_fma_f32 v106, v130, v134, v134
	v_fma_f32 v107, v131, v135, v135
	v_pk_fma_f32 v[108:109], v[132:133], v[136:137], v[136:137]
	v_rcp_f32_e32 v106, v106
	v_mfma_f32_16x16x32_bf16 v[54:57], v[74:77], v[114:117], v[54:57]
	v_rcp_f32_e32 v107, v107
	v_rcp_f32_e32 v108, v108
	v_rcp_f32_e32 v109, v109
	s_waitcnt vmcnt(1)
	v_mfma_f32_16x16x32_bf16 v[50:53], v[86:89], v[118:121], v[50:53]
	v_lshl_add_u64 v[110:111], v[110:111], 0, s[6:7]
	v_lshl_add_u64 v[110:111], v[110:111], 0, v[186:187]
	v_pk_mul_f32 v[112:113], v[46:47], s[20:21] op_sel_hi:[1,0]
	v_mfma_f32_16x16x32_bf16 v[54:57], v[82:85], v[118:121], v[54:57]
	v_mul_f32_e64 v114, v48, s20
	v_mul_f32_e64 v115, v49, s20
	v_pk_mul_f32 v[116:117], v[40:41], v[40:41]
	v_pk_mul_f32 v[118:119], v[38:39], v[38:39]
	s_waitcnt vmcnt(0)
; #define GAS __attribute__((address_space(1)))
; __device__ __forceinline__ v4u pack8(const float (&f)[8]) { v4u w; w.x = pk2(f[0], f[1]); w.y = pk2(f[2], f[3]); w.z = pk2(f[4], f[5]); w.w = pk2(f[6], f[7]); return w; }
; __device__ __forceinline__ float fexp2(float x) { return __builtin_amdgcn_exp2f(x); }
; __device__ __forceinline__ float frcp(float x) { return __builtin_amdgcn_rcpf(x); }
;     __device__ __forceinline__ void operator()(const af4 (&acc)[2][2][4][2], const pg8::Unit& u, int wr_, int wc_, int fr_, int fq_) const {
;     ...
;             for (int m = 0; m < 4; ++m) {
;                 if (ai == 0 && m == 0) load_raw(1);
;                 const int it = wr * 64 + m * 16 + fr;
;                 bf16x8 wf[4];
; #pragma unroll
;                 for (int ks = 0; ks < 4; ++ks) wf[ks] = *(const GAS bf16x8*)(wsg + (size_t)it * 128 + 32 * ks + 8 * fq);
;                 const float bsi = bs[grp * 128 + it];
;                 af4 vm[2] = {(af4){bsi, bsi, bsi, bsi}, (af4){bsi, bsi, bsi, bsi}};
; #pragma unroll
;                 for (int ks = 0; ks < 4; ++ks) {
; #pragma unroll
;                     for (int n = 0; n < 2; ++n) vm[n] = __builtin_amdgcn_mfma_f32_16x16x32_bf16(av[n][ks], wf[ks], vm[n], 0, 0, 0);
;                 }
;                 float o[8];
; #pragma unroll
;                 for (int n = 0; n < 2; ++n)
; #pragma unroll
;                     for (int e = 0; e < 4; e += 2) {
;                         const f32x2 uu = {acc[ai][0][m][n][e], acc[ai][0][m][n][e + 1]}, gg = {acc[ai][1][m][n][e], acc[ai][1][m][n][e + 1]}, vv = {vm[n][e], vm[n][e + 1]};
;                         const f32x2 ar = uu * (uu * uu * (-2.302208198f * 0.044715f) + (-2.302208198f));
;                         const f32x2 gs = gg * (-1.4426950408889634f);
;                         const f32x2 ea = {fexp2(ar.x), fexp2(ar.y)}, eb = {fexp2(gs.x), fexp2(gs.y)};
;                         const f32x2 q = eb + 1.0f, den = ea * q + q;
;                         const f32x2 r = {frcp(den.x), frcp(den.y)};
;                         const f32x2 w = (uu * gg) * vv * r;
;                         o[4 * n + e] = w.x; o[4 * n + e + 1] = w.y; }
;                 *(GAS v4u*)(Y + (size_t)(tok0 + it) * CW + chbase + 32 * wc + 8 * fq) = pack8(o);
	v_mfma_f32_16x16x32_bf16 v[50:53], v[90:93], v[122:125], v[50:53]
	v_mul_f32_e64 v120, v34, s20
	v_mul_f32_e64 v121, v35, s20
	v_pk_fma_f32 v[116:117], v[116:117], s[16:17], v[196:197] op_sel_hi:[1,0,0] neg_lo:[1,0,0] neg_hi:[1,0,0]
	v_pk_mul_f32 v[46:47], v[42:43], v[46:47]
	v_mfma_f32_16x16x32_bf16 v[54:57], v[94:97], v[122:125], v[54:57]
	v_mul_f32_e64 v122, v38, v34
	v_mul_f32_e64 v123, v39, v35
	s_nop 0
	v_pk_mul_f32 v[50:51], v[62:63], v[50:51]
	v_pk_mul_f32 v[52:53], v[64:65], v[52:53]
	v_pk_mul_f32 v[50:51], v[58:59], v[50:51]
	v_pk_mul_f32 v[52:53], v[60:61], v[52:53]
	s_nop 0
	v_pk_mul_f32 v[54:55], v[138:139], v[54:55]
	v_pk_mul_f32 v[56:57], v[140:141], v[56:57]
	v_pk_mul_f32 v[54:55], v[106:107], v[54:55]
	v_pk_mul_f32 v[56:57], v[108:109], v[56:57]
	v_cvt_pk_bf16_f32 v50, v50, v51
	v_cvt_pk_bf16_f32 v51, v52, v53
	v_cvt_pk_bf16_f32 v52, v54, v55
	v_pk_mul_f32 v[34:35], v[36:37], s[20:21] op_sel_hi:[1,0]
	v_cvt_pk_bf16_f32 v53, v56, v57
	global_store_dwordx4 v[110:111], v[50:53], off
	global_load_dword v50, v[200:201], off offset:64
	s_nop 0
	global_load_dwordx4 v[54:57], v[216:217], off
	global_load_dwordx4 v[58:61], v[216:217], off offset:64
	global_load_dwordx4 v[62:65], v[216:217], off offset:128
	global_load_dwordx4 v[106:109], v[216:217], off offset:192
	v_pk_mul_f32 v[52:53], v[44:45], v[44:45]
	v_pk_mul_f32 v[110:111], v[42:43], v[42:43]
	v_pk_mul_f32 v[124:125], v[40:41], v[36:37]
	v_pk_fma_f32 v[36:37], v[110:111], s[16:17], v[196:197] op_sel_hi:[1,0,0] neg_lo:[1,0,0] neg_hi:[1,0,0]
	v_pk_fma_f32 v[52:53], v[52:53], s[16:17], v[196:197] op_sel_hi:[1,0,0] neg_lo:[1,0,0] neg_hi:[1,0,0]
	v_exp_f32_e32 v110, v112
	v_exp_f32_e32 v111, v113
	v_exp_f32_e32 v112, v114
	v_exp_f32_e32 v113, v115
	v_pk_fma_f32 v[114:115], v[118:119], s[16:17], v[196:197] op_sel_hi:[1,0,0] neg_lo:[1,0,0] neg_hi:[1,0,0]
	v_exp_f32_e32 v118, v120
	v_exp_f32_e32 v119, v121
	v_exp_f32_e32 v120, v34
	v_exp_f32_e32 v121, v35
	v_pk_mul_f32 v[34:35], v[42:43], v[36:37]
	v_pk_mul_f32 v[36:37], v[44:45], v[52:53]
	v_pk_mul_f32 v[48:49], v[44:45], v[48:49]
	v_pk_mul_f32 v[38:39], v[38:39], v[114:115]
	v_pk_mul_f32 v[40:41], v[40:41], v[116:117]
	v_exp_f32_e32 v42, v34
	v_exp_f32_e32 v43, v35
	v_exp_f32_e32 v44, v36
	v_exp_f32_e32 v45, v37
	v_exp_f32_e32 v114, v38
	v_exp_f32_e32 v115, v39
	v_exp_f32_e32 v116, v40
	v_exp_f32_e32 v117, v41
	v_pk_add_f32 v[110:111], v[110:111], 1.0 op_sel_hi:[1,0]
	v_pk_add_f32 v[112:113], v[112:113], 1.0 op_sel_hi:[1,0]
	v_pk_add_f32 v[118:119], v[118:119], 1.0 op_sel_hi:[1,0]
	v_pk_add_f32 v[120:121], v[120:121], 1.0 op_sel_hi:[1,0]
	v_pk_fma_f32 v[42:43], v[42:43], v[110:111], v[110:111]
	v_pk_fma_f32 v[44:45], v[44:45], v[112:113], v[112:113]
	v_rcp_f32_e32 v42, v42
	v_rcp_f32_e32 v43, v43
	v_rcp_f32_e32 v44, v44
	v_rcp_f32_e32 v45, v45
	s_waitcnt vmcnt(4)
	v_mov_b32_e32 v51, v50
	v_mov_b32_e32 v52, v50
	v_mov_b32_e32 v53, v50
	s_waitcnt vmcnt(3)
	s_nop 0
	v_mfma_f32_16x16x32_bf16 v[34:37], v[70:73], v[54:57], v[50:53]
	v_mfma_f32_16x16x32_bf16 v[38:41], v[66:69], v[54:57], v[50:53]
	v_add_u32_e32 v54, s23, v212
	v_mad_i64_i32 v[54:55], s[26:27], v54, s61, v[198:199]
	s_waitcnt vmcnt(2)
	v_mfma_f32_16x16x32_bf16 v[34:37], v[78:81], v[58:61], v[34:37]
	v_fma_f32 v50, v114, v118, v118
	v_fma_f32 v51, v115, v119, v119
	v_pk_fma_f32 v[52:53], v[116:117], v[120:121], v[120:121]
	v_rcp_f32_e32 v50, v50
	v_mfma_f32_16x16x32_bf16 v[38:41], v[74:77], v[58:61], v[38:41]
	v_rcp_f32_e32 v51, v51
	v_rcp_f32_e32 v52, v52
	v_rcp_f32_e32 v53, v53
	s_waitcnt vmcnt(1)
	v_mfma_f32_16x16x32_bf16 v[34:37], v[86:89], v[62:65], v[34:37]
	v_lshl_add_u64 v[54:55], v[54:55], 0, s[40:41]
	v_lshl_add_u64 v[54:55], v[54:55], 0, s[6:7]
	v_lshl_add_u64 v[54:55], v[54:55], 0, v[186:187]
	v_mfma_f32_16x16x32_bf16 v[38:41], v[82:85], v[62:65], v[38:41]
	v_mul_f32_e64 v56, v30, s20
	v_mul_f32_e64 v57, v31, s20
	v_pk_mul_f32 v[58:59], v[32:33], s[20:21] op_sel_hi:[1,0]
	v_pk_mul_f32 v[60:61], v[24:25], v[24:25]
	s_waitcnt vmcnt(0)
	v_mfma_f32_16x16x32_bf16 v[34:37], v[90:93], v[106:109], v[34:37]
	v_mul_f32_e64 v62, v22, v22
	v_mul_f32_e64 v63, v23, v23
	v_pk_mul_f32 v[64:65], v[18:19], s[20:21] op_sel_hi:[1,0]
	v_pk_fma_f32 v[60:61], v[60:61], s[16:17], v[196:197] op_sel_hi:[1,0,0] neg_lo:[1,0,0] neg_hi:[1,0,0]
	v_mfma_f32_16x16x32_bf16 v[38:41], v[94:97], v[106:109], v[38:41]
	v_mul_f32_e64 v106, v24, v20
	v_mul_f32_e64 v107, v25, v21
	s_nop 0
	v_pk_mul_f32 v[34:35], v[46:47], v[34:35]
	v_pk_mul_f32 v[36:37], v[48:49], v[36:37]
	v_pk_mul_f32 v[34:35], v[42:43], v[34:35]
	v_pk_mul_f32 v[36:37], v[44:45], v[36:37]
	s_nop 0
	v_pk_mul_f32 v[38:39], v[122:123], v[38:39]
	v_pk_mul_f32 v[40:41], v[124:125], v[40:41]
	v_pk_mul_f32 v[38:39], v[50:51], v[38:39]
	v_pk_mul_f32 v[40:41], v[52:53], v[40:41]
	v_cvt_pk_bf16_f32 v34, v34, v35
	v_cvt_pk_bf16_f32 v35, v36, v37
	v_cvt_pk_bf16_f32 v36, v38, v39
	v_pk_mul_f32 v[30:31], v[26:27], v[30:31]
	v_cvt_pk_bf16_f32 v37, v40, v41
	global_store_dwordx4 v[54:55], v[34:37], off
	global_load_dword v34, v[200:201], off offset:128
	s_nop 0
	global_load_dwordx4 v[38:41], v[102:103], off
	global_load_dwordx4 v[42:45], v[102:103], off offset:64
	global_load_dwordx4 v[46:49], v[102:103], off offset:128
	global_load_dwordx4 v[50:53], v[102:103], off offset:192
	v_pk_mul_f32 v[36:37], v[28:29], v[28:29]
	v_pk_mul_f32 v[54:55], v[26:27], v[26:27]
	v_pk_mul_f32 v[102:103], v[22:23], v[18:19]
	v_pk_mul_f32 v[18:19], v[20:21], s[20:21] op_sel_hi:[1,0]
	v_pk_fma_f32 v[20:21], v[54:55], s[16:17], v[196:197] op_sel_hi:[1,0,0] neg_lo:[1,0,0] neg_hi:[1,0,0]
	v_pk_fma_f32 v[36:37], v[36:37], s[16:17], v[196:197] op_sel_hi:[1,0,0] neg_lo:[1,0,0] neg_hi:[1,0,0]
	v_exp_f32_e32 v54, v56
	v_exp_f32_e32 v55, v57
	v_exp_f32_e32 v56, v58
	v_exp_f32_e32 v57, v59
	v_pk_fma_f32 v[58:59], v[62:63], s[16:17], v[196:197] op_sel_hi:[1,0,0] neg_lo:[1,0,0] neg_hi:[1,0,0]
	v_exp_f32_e32 v62, v64
	v_exp_f32_e32 v63, v65
	v_exp_f32_e32 v64, v18
	v_exp_f32_e32 v65, v19
	v_pk_mul_f32 v[18:19], v[26:27], v[20:21]
	v_pk_mul_f32 v[20:21], v[28:29], v[36:37]
	v_pk_mul_f32 v[32:33], v[28:29], v[32:33]
	v_pk_mul_f32 v[22:23], v[22:23], v[58:59]
	v_pk_mul_f32 v[24:25], v[24:25], v[60:61]
	v_exp_f32_e32 v26, v18
	v_exp_f32_e32 v27, v19
	v_exp_f32_e32 v28, v20
	v_exp_f32_e32 v29, v21
	v_exp_f32_e32 v58, v22
	v_exp_f32_e32 v59, v23
	v_exp_f32_e32 v60, v24
	v_exp_f32_e32 v61, v25
	v_pk_add_f32 v[54:55], v[54:55], 1.0 op_sel_hi:[1,0]
	v_pk_add_f32 v[56:57], v[56:57], 1.0 op_sel_hi:[1,0]
	v_pk_add_f32 v[62:63], v[62:63], 1.0 op_sel_hi:[1,0]
	v_pk_add_f32 v[64:65], v[64:65], 1.0 op_sel_hi:[1,0]
	v_pk_fma_f32 v[26:27], v[26:27], v[54:55], v[54:55]
	v_pk_fma_f32 v[28:29], v[28:29], v[56:57], v[56:57]
	v_rcp_f32_e32 v26, v26
	v_rcp_f32_e32 v27, v27
	v_rcp_f32_e32 v28, v28
	v_rcp_f32_e32 v29, v29
	s_waitcnt vmcnt(4)
; template <class Epi, class Sched, bool ALIGN_EPI = false, bool SP2 = false>
; __device__ __forceinline__ void gemm_phase(PG8_LAS unsigned char* lds, const Gemm g, const Sched& S, const Epi& E) {
;     ...
;         if constexpr (ALIGN_EPI) { if (wr == 0) PG8_BAR; }
;         E(acc, cur, wr, wc, fr, fq);
;         if (!has_next) break;
; #pragma unroll
;         for (int a = 0; a < 2; ++a)
; #pragma unroll
;             for (int b = 0; b < 2; ++b)
; #pragma unroll
;                 for (int m = 0; m < 4; ++m)
; #pragma unroll
;     __device__ __forceinline__ void operator()(const af4 (&acc)[2][2][4][2], const pg8::Unit& u, int wr_, int wc_, int fr_, int fq_) const {
;     ...
;             for (int m = 0; m < 4; ++m) {
;                 if (ai == 0 && m == 0) load_raw(1);
;                 const int it = wr * 64 + m * 16 + fr;
;                 bf16x8 wf[4];
; #pragma unroll
;                 for (int ks = 0; ks < 4; ++ks) wf[ks] = *(const GAS bf16x8*)(wsg + (size_t)it * 128 + 32 * ks + 8 * fq);
;                 const float bsi = bs[grp * 128 + it];
;                 af4 vm[2] = {(af4){bsi, bsi, bsi, bsi}, (af4){bsi, bsi, bsi, bsi}};
; #pragma unroll
;                 for (int ks = 0; ks < 4; ++ks) {
; #pragma unroll
;                     for (int n = 0; n < 2; ++n) vm[n] = __builtin_amdgcn_mfma_f32_16x16x32_bf16(av[n][ks], wf[ks], vm[n], 0, 0, 0);
;                 }
;                 float o[8];
; #pragma unroll
;                 for (int n = 0; n < 2; ++n)
; #pragma unroll
;                     for (int e = 0; e < 4; e += 2) {
;                         const f32x2 uu = {acc[ai][0][m][n][e], acc[ai][0][m][n][e + 1]}, gg = {acc[ai][1][m][n][e], acc[ai][1][m][n][e + 1]}, vv = {vm[n][e], vm[n][e + 1]};
;                         const f32x2 ar = uu * (uu * uu * (-2.302208198f * 0.044715f) + (-2.302208198f));
;                         const f32x2 gs = gg * (-1.4426950408889634f);
;                         const f32x2 ea = {fexp2(ar.x), fexp2(ar.y)}, eb = {fexp2(gs.x), fexp2(gs.y)};
;                         const f32x2 q = eb + 1.0f, den = ea * q + q;
;                         const f32x2 r = {frcp(den.x), frcp(den.y)};
;                         const f32x2 w = (uu * gg) * vv * r;
;                         o[4 * n + e] = w.x; o[4 * n + e + 1] = w.y; }
;                 *(GAS v4u*)(Y + (size_t)(tok0 + it) * CW + chbase + 32 * wc + 8 * fq) = pack8(o);
	v_mov_b32_e32 v35, v34
	v_mov_b32_e32 v36, v34
	v_mov_b32_e32 v37, v34
	s_waitcnt vmcnt(3)
	s_nop 0
	v_mfma_f32_16x16x32_bf16 v[18:21], v[70:73], v[38:41], v[34:37]
	v_mfma_f32_16x16x32_bf16 v[22:25], v[66:69], v[38:41], v[34:37]
	v_add_u32_e32 v38, s23, v98
	v_mad_i64_i32 v[38:39], s[26:27], v38, s61, v[198:199]
	s_waitcnt vmcnt(2)
	v_mfma_f32_16x16x32_bf16 v[18:21], v[78:81], v[42:45], v[18:21]
	v_fma_f32 v34, v58, v62, v62
	v_fma_f32 v35, v59, v63, v63
	v_pk_fma_f32 v[36:37], v[60:61], v[64:65], v[64:65]
	v_rcp_f32_e32 v34, v34
	v_mfma_f32_16x16x32_bf16 v[22:25], v[74:77], v[42:45], v[22:25]
	v_rcp_f32_e32 v35, v35
	v_rcp_f32_e32 v36, v36
	v_rcp_f32_e32 v37, v37
	s_waitcnt vmcnt(1)
	v_mfma_f32_16x16x32_bf16 v[18:21], v[86:89], v[46:49], v[18:21]
	v_lshl_add_u64 v[38:39], v[38:39], 0, s[40:41]
	v_lshl_add_u64 v[38:39], v[38:39], 0, s[6:7]
	v_lshl_add_u64 v[38:39], v[38:39], 0, v[186:187]
	v_mfma_f32_16x16x32_bf16 v[22:25], v[82:85], v[46:49], v[22:25]
	v_mul_f32_e64 v40, v14, s20
	v_mul_f32_e64 v41, v15, s20
	v_pk_mul_f32 v[42:43], v[16:17], s[20:21] op_sel_hi:[1,0]
	v_pk_mul_f32 v[44:45], v[8:9], v[8:9]
	s_waitcnt vmcnt(0)
	v_mfma_f32_16x16x32_bf16 v[18:21], v[90:93], v[50:53], v[18:21]
	v_mul_f32_e64 v46, v6, v6
	v_mul_f32_e64 v47, v7, v7
	v_pk_mul_f32 v[48:49], v[2:3], s[20:21] op_sel_hi:[1,0]
	v_pk_fma_f32 v[44:45], v[44:45], s[16:17], v[196:197] op_sel_hi:[1,0,0] neg_lo:[1,0,0] neg_hi:[1,0,0]
	v_mfma_f32_16x16x32_bf16 v[22:25], v[94:97], v[50:53], v[22:25]
	v_mul_f32_e64 v50, v6, v2
	v_mul_f32_e64 v51, v7, v3
	s_nop 0
	v_pk_mul_f32 v[18:19], v[30:31], v[18:19]
	v_pk_mul_f32 v[20:21], v[32:33], v[20:21]
	v_pk_mul_f32 v[18:19], v[26:27], v[18:19]
	v_pk_mul_f32 v[20:21], v[28:29], v[20:21]
	s_nop 0
	v_pk_mul_f32 v[22:23], v[102:103], v[22:23]
	v_pk_mul_f32 v[24:25], v[106:107], v[24:25]
	v_pk_mul_f32 v[22:23], v[34:35], v[22:23]
	v_pk_mul_f32 v[24:25], v[36:37], v[24:25]
	v_cvt_pk_bf16_f32 v18, v18, v19
	v_cvt_pk_bf16_f32 v19, v20, v21
	v_cvt_pk_bf16_f32 v20, v22, v23
	v_pk_mul_f32 v[2:3], v[4:5], s[20:21] op_sel_hi:[1,0]
	v_cvt_pk_bf16_f32 v21, v24, v25
	global_store_dwordx4 v[38:39], v[18:21], off
	global_load_dword v18, v[200:201], off offset:192
	s_nop 0
	global_load_dwordx4 v[22:25], v[104:105], off
	global_load_dwordx4 v[26:29], v[104:105], off offset:64
	global_load_dwordx4 v[30:33], v[104:105], off offset:128
	global_load_dwordx4 v[34:37], v[104:105], off offset:192
	v_pk_mul_f32 v[20:21], v[12:13], v[12:13]
	v_pk_mul_f32 v[38:39], v[10:11], v[10:11]
	v_pk_mul_f32 v[52:53], v[8:9], v[4:5]
	v_pk_fma_f32 v[4:5], v[38:39], s[16:17], v[196:197] op_sel_hi:[1,0,0] neg_lo:[1,0,0] neg_hi:[1,0,0]
	v_pk_fma_f32 v[20:21], v[20:21], s[16:17], v[196:197] op_sel_hi:[1,0,0] neg_lo:[1,0,0] neg_hi:[1,0,0]
	v_exp_f32_e32 v38, v40
	v_exp_f32_e32 v39, v41
	v_exp_f32_e32 v40, v42
	v_exp_f32_e32 v41, v43
	v_pk_fma_f32 v[42:43], v[46:47], s[16:17], v[196:197] op_sel_hi:[1,0,0] neg_lo:[1,0,0] neg_hi:[1,0,0]
	v_exp_f32_e32 v46, v48
	v_exp_f32_e32 v47, v49
	v_exp_f32_e32 v48, v2
	v_exp_f32_e32 v49, v3
	v_pk_mul_f32 v[2:3], v[10:11], v[4:5]
	v_pk_mul_f32 v[4:5], v[12:13], v[20:21]
	v_pk_mul_f32 v[14:15], v[10:11], v[14:15]
	v_pk_mul_f32 v[16:17], v[12:13], v[16:17]
	v_pk_mul_f32 v[6:7], v[6:7], v[42:43]
	v_pk_mul_f32 v[8:9], v[8:9], v[44:45]
	v_exp_f32_e32 v10, v2
	v_exp_f32_e32 v11, v3
	v_exp_f32_e32 v12, v4
	v_exp_f32_e32 v13, v5
	v_exp_f32_e32 v42, v6
	v_exp_f32_e32 v43, v7
	v_exp_f32_e32 v44, v8
	v_exp_f32_e32 v45, v9
	v_pk_add_f32 v[38:39], v[38:39], 1.0 op_sel_hi:[1,0]
	v_pk_add_f32 v[40:41], v[40:41], 1.0 op_sel_hi:[1,0]
	v_pk_add_f32 v[46:47], v[46:47], 1.0 op_sel_hi:[1,0]
	v_pk_add_f32 v[48:49], v[48:49], 1.0 op_sel_hi:[1,0]
	v_pk_fma_f32 v[10:11], v[10:11], v[38:39], v[38:39]
	v_pk_fma_f32 v[12:13], v[12:13], v[40:41], v[40:41]
	v_rcp_f32_e32 v10, v10
	v_rcp_f32_e32 v11, v11
	v_rcp_f32_e32 v12, v12
	v_rcp_f32_e32 v13, v13
	s_waitcnt vmcnt(4)
	v_mov_b32_e32 v19, v18
	v_mov_b32_e32 v20, v18
	v_mov_b32_e32 v21, v18
	s_waitcnt vmcnt(3)
	s_nop 0
	v_mfma_f32_16x16x32_bf16 v[2:5], v[70:73], v[22:25], v[18:21]
	v_mfma_f32_16x16x32_bf16 v[6:9], v[66:69], v[22:25], v[18:21]
	v_add_u32_e32 v22, s23, v100
	v_mad_i64_i32 v[22:23], s[4:5], v22, s61, v[198:199]
	s_waitcnt vmcnt(2)
	v_mfma_f32_16x16x32_bf16 v[2:5], v[78:81], v[26:29], v[2:5]
	v_fma_f32 v18, v42, v46, v46
	v_fma_f32 v19, v43, v47, v47
	v_pk_fma_f32 v[20:21], v[44:45], v[48:49], v[48:49]
	v_rcp_f32_e32 v18, v18
	v_mfma_f32_16x16x32_bf16 v[6:9], v[74:77], v[26:29], v[6:9]
	v_rcp_f32_e32 v19, v19
	v_rcp_f32_e32 v20, v20
	v_rcp_f32_e32 v21, v21
	s_waitcnt vmcnt(1)
	v_mfma_f32_16x16x32_bf16 v[2:5], v[86:89], v[30:33], v[2:5]
	v_lshl_add_u64 v[22:23], v[22:23], 0, s[40:41]
	v_lshl_add_u64 v[22:23], v[22:23], 0, s[6:7]
	v_lshl_add_u64 v[22:23], v[22:23], 0, v[186:187]
	v_mfma_f32_16x16x32_bf16 v[6:9], v[82:85], v[30:33], v[6:9]
	s_mov_b64 s[4:5], -1
	s_waitcnt vmcnt(0)
	v_mfma_f32_16x16x32_bf16 v[2:5], v[90:93], v[34:37], v[2:5]
	v_mfma_f32_16x16x32_bf16 v[6:9], v[94:97], v[34:37], v[6:9]
	s_nop 6
	v_mul_f32_e64 v2, v14, v2
	v_mul_f32_e64 v3, v15, v3
	v_pk_mul_f32 v[4:5], v[16:17], v[4:5]
	v_pk_mul_f32 v[6:7], v[50:51], v[6:7]
	v_pk_mul_f32 v[8:9], v[52:53], v[8:9]
	v_pk_mul_f32 v[2:3], v[10:11], v[2:3]
	v_pk_mul_f32 v[4:5], v[12:13], v[4:5]
	v_pk_mul_f32 v[6:7], v[18:19], v[6:7]
	v_pk_mul_f32 v[8:9], v[20:21], v[8:9]
	v_cvt_pk_bf16_f32 v2, v2, v3
	v_cvt_pk_bf16_f32 v3, v4, v5
	v_cvt_pk_bf16_f32 v4, v6, v7
	s_nop 0
	v_cvt_pk_bf16_f32 v5, v8, v9
	global_store_dwordx4 v[22:23], v[2:5], off
	s_cbranch_vccnz .LBB0_1123
	s_andn2_b64 vcc, exec, s[10:11]
	s_cbranch_vccnz .LBB0_1122
	s_barrier
	s_branch .LBB0_1122
